# F1: step-4/5 fragment builders rewritten: wave-uniform fragment addressing (per-lane bases + scalar offsets), 2-deep software pipelining of LDS reads, re-dealt so waves sharing a SIMD with the inverti
# speedup vs baseline: 1.0139x; 1.0005x over previous
.LBB0_271:
	s_or_b64 exec, exec, s[16:17]
	s_lshl_b64 s[0:1], s[10:11], 2
	s_add_u32 s0, s34, s0
	s_addc_u32 s1, s35, s1
	v_lshlrev_b32_e32 v128, 2, v215
	v_lshl_add_u64 v[0:1], s[0:1], 0, v[128:129]
	global_load_dwordx4 v[162:165], v128, s[0:1] offset:48
	global_load_dwordx4 v[150:153], v128, s[0:1] offset:32
	global_load_dwordx4 v[130:133], v128, s[0:1] offset:16
	global_load_dwordx4 v[112:115], v128, s[0:1]
	s_mov_b64 s[0:1], 0x4800
	v_lshl_add_u64 v[2:3], v[0:1], 0, s[0:1]
	s_movk_i32 s0, 0x4000
	v_add_co_u32_e32 v4, vcc, s0, v0
	s_mov_b64 s[0:1], 0x9000
	s_nop 0
	v_addc_co_u32_e32 v5, vcc, 0, v1, vcc
	global_load_dwordx4 v[116:119], v[4:5], off offset:2048
	global_load_dwordx4 v[166:169], v[2:3], off offset:48
	global_load_dwordx4 v[154:157], v[2:3], off offset:32
	global_load_dwordx4 v[138:141], v[2:3], off offset:16
	v_lshl_add_u64 v[2:3], v[0:1], 0, s[0:1]
	s_mov_b32 s0, 0x9000
	v_add_co_u32_e32 v0, vcc, s0, v0
	v_readlane_b32 s6, v254, 15
	s_nop 0
	v_addc_co_u32_e32 v1, vcc, 0, v1, vcc
	global_load_dwordx4 v[120:123], v[0:1], off
	global_load_dwordx4 v[170:173], v[2:3], off offset:48
	global_load_dwordx4 v[158:161], v[2:3], off offset:32
	global_load_dwordx4 v[142:145], v[2:3], off offset:16
	v_lshlrev_b32_e32 v0, 4, v216
	v_mov_b32_e32 v1, 0
	v_mul_u32_u24_e32 v10, 0x110, v188
	v_lshlrev_b32_e32 v11, 3, v189
	v_add_u32_e32 v2, v10, v11
	v_add_u32_e32 v2, 0x4400, v2
	v_lshlrev_b32_e32 v3, 2, v188
	v_add_u32_e32 v3, 0x22c00, v3
	v_mul_u32_u24_e32 v10, 0x90, v188
	v_add_u32_e32 v10, v10, v11
	v_add_u32_e32 v7, 0x1a000, v10
	v_lshrrev_b32_e32 v11, 4, v188
	v_lshl_add_u32 v4, v11, 4, v10
	v_add_u32_e32 v4, 0x8800, v4
	v_xor_b32_e32 v11, 1, v11
	v_lshl_add_u32 v5, v11, 4, v10
	v_add_u32_e32 v5, 0x8800, v5
	v_lshlrev_b32_e32 v6, 4, v189
	v_add_u32_e32 v6, 0x22c00, v6
	v_readlane_b32 s10, v254, 15
	v_readlane_b32 s11, v254, 16
	v_readlane_b32 s16, v254, 19
	v_readlane_b32 s17, v254, 20
	v_readlane_b32 s26, v254, 21
	v_readlane_b32 s27, v254, 22
	s_add_u32 s10, s10, s4
	s_addc_u32 s11, s11, s5
	s_add_u32 s16, s16, s4
	s_addc_u32 s17, s17, s5
	s_add_u32 s26, s26, s4
	s_addc_u32 s27, s27, s5
	s_lshr_b32 s0, s87, 6
	s_and_b32 s1, s0, 6
	s_cmp_eq_u32 s1, 4
	s_cbranch_scc1 .Lf1_clsB
	s_and_b32 s1, s0, 1
	s_lshr_b32 s0, s0, 2
	s_lshl_b32 s0, s0, 1
	s_add_i32 s1, s1, s0
	s_mul_i32 s0, s1, 3
	s_lshl_b32 s1, s1, 1
	s_add_i32 s42, s0, 0
	s_lshr_b32 s43, s42, 3
	s_mul_i32 s46, s43, 0x2200
	s_and_b32 s44, s42, 7
	s_lshl_b32 s44, s44, 5
	s_add_i32 s46, s46, s44
	s_lshl_b32 s43, s43, 7
	s_addk_i32 s43, 0x400
	v_add_u32_e32 v62, s46, v2
	v_add_u32_e32 v63, s43, v3
	ds_read2_b64 v[12:15], v62 offset1:2
	ds_read_b32 v16, v63
	s_add_i32 s42, s0, 1
	s_lshr_b32 s43, s42, 3
	s_mul_i32 s46, s43, 0x2200
	s_and_b32 s44, s42, 7
	s_lshl_b32 s44, s44, 5
	s_add_i32 s46, s46, s44
	s_lshl_b32 s43, s43, 7
	s_addk_i32 s43, 0x400
	v_add_u32_e32 v62, s46, v2
	v_add_u32_e32 v63, s43, v3
	ds_read2_b64 v[26:29], v62 offset1:2
	ds_read_b32 v30, v63
	s_add_i32 s42, s0, 2
	s_lshr_b32 s43, s42, 3
	s_mul_i32 s46, s43, 0x2200
	s_and_b32 s44, s42, 7
	s_lshl_b32 s44, s44, 5
	s_add_i32 s46, s46, s44
	s_lshl_b32 s43, s43, 7
	s_addk_i32 s43, 0x400
	v_add_u32_e32 v62, s46, v2
	v_add_u32_e32 v63, s43, v3
	ds_read2_b64 v[40:43], v62 offset1:2
	ds_read_b32 v44, v63
	s_add_i32 s42, s0, 0
	s_lshl_b32 s42, s42, 10
	s_add_u32 s6, s10, s42
	s_addc_u32 s7, s11, 0
	v_lshl_add_u64 v[8:9], v[0:1], 0, s[6:7]
	s_waitcnt lgkmcnt(4)
	v_lshlrev_b32_e32 v54, 16, v12
	v_and_b32_e32 v55, 0xffff0000, v12
	v_lshlrev_b32_e32 v56, 16, v13
	v_and_b32_e32 v57, 0xffff0000, v13
	v_lshlrev_b32_e32 v58, 16, v14
	v_and_b32_e32 v59, 0xffff0000, v14
	v_lshlrev_b32_e32 v60, 16, v15
	v_and_b32_e32 v61, 0xffff0000, v15
	v_pk_mul_f32 v[54:55], v[16:17], v[54:55] op_sel_hi:[0,1]
	v_pk_mul_f32 v[56:57], v[16:17], v[56:57] op_sel_hi:[0,1]
	v_pk_mul_f32 v[58:59], v[16:17], v[58:59] op_sel_hi:[0,1]
	v_pk_mul_f32 v[60:61], v[16:17], v[60:61] op_sel_hi:[0,1]
	v_cvt_pk_bf16_f32 v12, v54, v55
	v_cvt_pk_bf16_f32 v13, v56, v57
	v_cvt_pk_bf16_f32 v14, v58, v59
	v_cvt_pk_bf16_f32 v15, v60, v61
	global_store_dwordx4 v[8:9], v[12:15], off nt
	s_add_i32 s42, s0, 0
	s_lshr_b32 s43, s42, 2
	s_and_b32 s44, s42, 3
	s_lshl_b32 s46, s44, 1
	s_lshl_b32 s6, s43, 1
	s_xor_b32 s46, s46, s6
	s_lshl_b32 s46, s46, 4
	s_mul_i32 s43, s43, 0x1200
	s_add_i32 s46, s46, s43
	s_lshl_b32 s44, s44, 6
	s_addk_i32 s44, 0x600
	v_add_u32_e32 v62, s46, v4
	v_add_u32_e32 v63, s46, v5
	ds_read_b64 v[12:13], v62
	ds_read_b64 v[14:15], v63
	v_add_u32_e32 v62, s44, v6
	ds_read_b128 v[16:19], v62
	ds_read_b128 v[20:23], v62 offset:32
	s_add_i32 s42, s0, 1
	s_lshl_b32 s42, s42, 10
	s_add_u32 s6, s10, s42
	s_addc_u32 s7, s11, 0
	v_lshl_add_u64 v[8:9], v[0:1], 0, s[6:7]
	s_waitcnt lgkmcnt(6)
	v_lshlrev_b32_e32 v54, 16, v26
	v_and_b32_e32 v55, 0xffff0000, v26
	v_lshlrev_b32_e32 v56, 16, v27
	v_and_b32_e32 v57, 0xffff0000, v27
	v_lshlrev_b32_e32 v58, 16, v28
	v_and_b32_e32 v59, 0xffff0000, v28
	v_lshlrev_b32_e32 v60, 16, v29
	v_and_b32_e32 v61, 0xffff0000, v29
	v_pk_mul_f32 v[54:55], v[30:31], v[54:55] op_sel_hi:[0,1]
	v_pk_mul_f32 v[56:57], v[30:31], v[56:57] op_sel_hi:[0,1]
	v_pk_mul_f32 v[58:59], v[30:31], v[58:59] op_sel_hi:[0,1]
	v_pk_mul_f32 v[60:61], v[30:31], v[60:61] op_sel_hi:[0,1]
	v_cvt_pk_bf16_f32 v26, v54, v55
	v_cvt_pk_bf16_f32 v27, v56, v57
	v_cvt_pk_bf16_f32 v28, v58, v59
	v_cvt_pk_bf16_f32 v29, v60, v61
	global_store_dwordx4 v[8:9], v[26:29], off nt
	s_add_i32 s42, s0, 1
	s_lshr_b32 s43, s42, 2
	s_and_b32 s44, s42, 3
	s_lshl_b32 s46, s44, 1
	s_lshl_b32 s6, s43, 1
	s_xor_b32 s46, s46, s6
	s_lshl_b32 s46, s46, 4
	s_mul_i32 s43, s43, 0x1200
	s_add_i32 s46, s46, s43
	s_lshl_b32 s44, s44, 6
	s_addk_i32 s44, 0x600
	v_add_u32_e32 v62, s46, v4
	v_add_u32_e32 v63, s46, v5
	ds_read_b64 v[26:27], v62
	ds_read_b64 v[28:29], v63
	v_add_u32_e32 v62, s44, v6
	ds_read_b128 v[30:33], v62
	ds_read_b128 v[34:37], v62 offset:32
	s_add_i32 s42, s0, 2
	s_lshl_b32 s42, s42, 10
	s_add_u32 s6, s10, s42
	s_addc_u32 s7, s11, 0
	v_lshl_add_u64 v[8:9], v[0:1], 0, s[6:7]
	s_waitcnt lgkmcnt(8)
	v_lshlrev_b32_e32 v54, 16, v40
	v_and_b32_e32 v55, 0xffff0000, v40
	v_lshlrev_b32_e32 v56, 16, v41
	v_and_b32_e32 v57, 0xffff0000, v41
	v_lshlrev_b32_e32 v58, 16, v42
	v_and_b32_e32 v59, 0xffff0000, v42
	v_lshlrev_b32_e32 v60, 16, v43
	v_and_b32_e32 v61, 0xffff0000, v43
	v_pk_mul_f32 v[54:55], v[44:45], v[54:55] op_sel_hi:[0,1]
	v_pk_mul_f32 v[56:57], v[44:45], v[56:57] op_sel_hi:[0,1]
	v_pk_mul_f32 v[58:59], v[44:45], v[58:59] op_sel_hi:[0,1]
	v_pk_mul_f32 v[60:61], v[44:45], v[60:61] op_sel_hi:[0,1]
	v_cvt_pk_bf16_f32 v40, v54, v55
	v_cvt_pk_bf16_f32 v41, v56, v57
	v_cvt_pk_bf16_f32 v42, v58, v59
	v_cvt_pk_bf16_f32 v43, v60, v61
	global_store_dwordx4 v[8:9], v[40:43], off nt
	s_add_i32 s42, s0, 2
	s_lshr_b32 s43, s42, 2
	s_and_b32 s44, s42, 3
	s_lshl_b32 s46, s44, 1
	s_lshl_b32 s6, s43, 1
	s_xor_b32 s46, s46, s6
	s_lshl_b32 s46, s46, 4
	s_mul_i32 s43, s43, 0x1200
	s_add_i32 s46, s46, s43
	s_lshl_b32 s44, s44, 6
	s_addk_i32 s44, 0x600
	v_add_u32_e32 v62, s46, v4
	v_add_u32_e32 v63, s46, v5
	ds_read_b64 v[40:41], v62
	ds_read_b64 v[42:43], v63
	v_add_u32_e32 v62, s44, v6
	ds_read_b128 v[44:47], v62
	ds_read_b128 v[48:51], v62 offset:32
	s_add_i32 s42, s0, 0
	s_lshl_b32 s42, s42, 10
	s_add_u32 s6, s16, s42
	s_addc_u32 s7, s17, 0
	v_lshl_add_u64 v[8:9], v[0:1], 0, s[6:7]
	s_waitcnt lgkmcnt(8)
	v_lshlrev_b32_e32 v54, 16, v12
	v_and_b32_e32 v55, 0xffff0000, v12
	v_lshlrev_b32_e32 v56, 16, v13
	v_and_b32_e32 v57, 0xffff0000, v13
	v_lshlrev_b32_e32 v58, 16, v14
	v_and_b32_e32 v59, 0xffff0000, v14
	v_lshlrev_b32_e32 v60, 16, v15
	v_and_b32_e32 v61, 0xffff0000, v15
	v_pk_mul_f32 v[54:55], v[16:17], v[54:55]
	v_pk_mul_f32 v[56:57], v[18:19], v[56:57]
	v_pk_mul_f32 v[58:59], v[20:21], v[58:59]
	v_pk_mul_f32 v[60:61], v[22:23], v[60:61]
	v_cvt_pk_bf16_f32 v12, v54, v55
	v_cvt_pk_bf16_f32 v13, v56, v57
	v_cvt_pk_bf16_f32 v14, v58, v59
	v_cvt_pk_bf16_f32 v15, v60, v61
	global_store_dwordx4 v[8:9], v[12:15], off nt
	s_add_i32 s42, s1, 0
	s_lshr_b32 s43, s42, 2
	s_mul_i32 s46, s43, 0x1200
	s_and_b32 s44, s42, 3
	s_lshl_b32 s44, s44, 5
	s_add_i32 s46, s46, s44
	v_add_u32_e32 v62, s46, v7
	ds_read2_b64 v[12:15], v62 offset1:2
	s_add_i32 s42, s0, 1
	s_lshl_b32 s42, s42, 10
	s_add_u32 s6, s16, s42
	s_addc_u32 s7, s17, 0
	v_lshl_add_u64 v[8:9], v[0:1], 0, s[6:7]
	s_waitcnt lgkmcnt(5)
	v_lshlrev_b32_e32 v54, 16, v26
	v_and_b32_e32 v55, 0xffff0000, v26
	v_lshlrev_b32_e32 v56, 16, v27
	v_and_b32_e32 v57, 0xffff0000, v27
	v_lshlrev_b32_e32 v58, 16, v28
	v_and_b32_e32 v59, 0xffff0000, v28
	v_lshlrev_b32_e32 v60, 16, v29
	v_and_b32_e32 v61, 0xffff0000, v29
	v_pk_mul_f32 v[54:55], v[30:31], v[54:55]
	v_pk_mul_f32 v[56:57], v[32:33], v[56:57]
	v_pk_mul_f32 v[58:59], v[34:35], v[58:59]
	v_pk_mul_f32 v[60:61], v[36:37], v[60:61]
	v_cvt_pk_bf16_f32 v26, v54, v55
	v_cvt_pk_bf16_f32 v27, v56, v57
	v_cvt_pk_bf16_f32 v28, v58, v59
	v_cvt_pk_bf16_f32 v29, v60, v61
	global_store_dwordx4 v[8:9], v[26:29], off nt
	s_add_i32 s42, s1, 1
	s_lshr_b32 s43, s42, 2
	s_mul_i32 s46, s43, 0x1200
	s_and_b32 s44, s42, 3
	s_lshl_b32 s44, s44, 5
	s_add_i32 s46, s46, s44
	v_add_u32_e32 v62, s46, v7
	ds_read2_b64 v[26:29], v62 offset1:2
	s_add_i32 s42, s0, 2
	s_lshl_b32 s42, s42, 10
	s_add_u32 s6, s16, s42
	s_addc_u32 s7, s17, 0
	v_lshl_add_u64 v[8:9], v[0:1], 0, s[6:7]
	s_waitcnt lgkmcnt(2)
	v_lshlrev_b32_e32 v54, 16, v40
	v_and_b32_e32 v55, 0xffff0000, v40
	v_lshlrev_b32_e32 v56, 16, v41
	v_and_b32_e32 v57, 0xffff0000, v41
	v_lshlrev_b32_e32 v58, 16, v42
	v_and_b32_e32 v59, 0xffff0000, v42
	v_lshlrev_b32_e32 v60, 16, v43
	v_and_b32_e32 v61, 0xffff0000, v43
	v_pk_mul_f32 v[54:55], v[44:45], v[54:55]
	v_pk_mul_f32 v[56:57], v[46:47], v[56:57]
	v_pk_mul_f32 v[58:59], v[48:49], v[58:59]
	v_pk_mul_f32 v[60:61], v[50:51], v[60:61]
	v_cvt_pk_bf16_f32 v40, v54, v55
	v_cvt_pk_bf16_f32 v41, v56, v57
	v_cvt_pk_bf16_f32 v42, v58, v59
	v_cvt_pk_bf16_f32 v43, v60, v61
	global_store_dwordx4 v[8:9], v[40:43], off nt
	s_add_i32 s42, s0, 0
	s_lshr_b32 s43, s42, 3
	s_mul_i32 s46, s43, 0x2200
	s_and_b32 s44, s42, 7
	s_lshl_b32 s44, s44, 5
	s_add_i32 s46, s46, s44
	s_lshl_b32 s43, s43, 7
	s_addk_i32 s43, 0x500
	v_add_u32_e32 v62, s46, v2
	v_add_u32_e32 v63, s43, v3
	ds_read2_b64 v[40:43], v62 offset1:2
	ds_read_b32 v44, v63
	s_add_i32 s42, s1, 0
	s_lshl_b32 s42, s42, 10
	s_add_u32 s6, s26, s42
	s_addc_u32 s7, s27, 0
	v_lshl_add_u64 v[8:9], v[0:1], 0, s[6:7]
	s_waitcnt lgkmcnt(3)
	global_store_dwordx4 v[8:9], v[12:15], off nt
	s_add_i32 s42, s0, 1
	s_lshr_b32 s43, s42, 3
	s_mul_i32 s46, s43, 0x2200
	s_and_b32 s44, s42, 7
	s_lshl_b32 s44, s44, 5
	s_add_i32 s46, s46, s44
	s_lshl_b32 s43, s43, 7
	s_addk_i32 s43, 0x500
	v_add_u32_e32 v62, s46, v2
	v_add_u32_e32 v63, s43, v3
	ds_read2_b64 v[12:15], v62 offset1:2
	ds_read_b32 v16, v63
	s_add_i32 s42, s1, 1
	s_lshl_b32 s42, s42, 10
	s_add_u32 s6, s26, s42
	s_addc_u32 s7, s27, 0
	v_lshl_add_u64 v[8:9], v[0:1], 0, s[6:7]
	s_waitcnt lgkmcnt(4)
	global_store_dwordx4 v[8:9], v[26:29], off nt
	s_add_i32 s42, s0, 2
	s_lshr_b32 s43, s42, 3
	s_mul_i32 s46, s43, 0x2200
	s_and_b32 s44, s42, 7
	s_lshl_b32 s44, s44, 5
	s_add_i32 s46, s46, s44
	s_lshl_b32 s43, s43, 7
	s_addk_i32 s43, 0x500
	v_add_u32_e32 v62, s46, v2
	v_add_u32_e32 v63, s43, v3
	ds_read2_b64 v[26:29], v62 offset1:2
	ds_read_b32 v30, v63
	s_add_i32 s42, s0, 0
	s_lshl_b32 s42, s42, 10
	s_add_i32 s42, s42, 0x12000
	s_add_u32 s6, s10, s42
	s_addc_u32 s7, s11, 0
	v_lshl_add_u64 v[8:9], v[0:1], 0, s[6:7]
	s_waitcnt lgkmcnt(4)
	v_lshlrev_b32_e32 v54, 16, v40
	v_and_b32_e32 v55, 0xffff0000, v40
	v_lshlrev_b32_e32 v56, 16, v41
	v_and_b32_e32 v57, 0xffff0000, v41
	v_lshlrev_b32_e32 v58, 16, v42
	v_and_b32_e32 v59, 0xffff0000, v42
	v_lshlrev_b32_e32 v60, 16, v43
	v_and_b32_e32 v61, 0xffff0000, v43
	v_pk_mul_f32 v[54:55], v[44:45], v[54:55] op_sel_hi:[0,1]
	v_pk_mul_f32 v[56:57], v[44:45], v[56:57] op_sel_hi:[0,1]
	v_pk_mul_f32 v[58:59], v[44:45], v[58:59] op_sel_hi:[0,1]
	v_pk_mul_f32 v[60:61], v[44:45], v[60:61] op_sel_hi:[0,1]
	v_cvt_pk_bf16_f32 v40, v54, v55
	v_cvt_pk_bf16_f32 v41, v56, v57
	v_cvt_pk_bf16_f32 v42, v58, v59
	v_cvt_pk_bf16_f32 v43, v60, v61
	global_store_dwordx4 v[8:9], v[40:43], off nt
	s_add_i32 s42, s0, 0
	s_lshr_b32 s43, s42, 2
	s_and_b32 s44, s42, 3
	s_lshl_b32 s46, s44, 1
	s_lshl_b32 s6, s43, 1
	s_xor_b32 s46, s46, s6
	s_lshl_b32 s46, s46, 4
	s_mul_i32 s43, s43, 0x1200
	s_add_i32 s46, s46, s43
	s_lshl_b32 s44, s44, 6
	s_addk_i32 s44, 0x700
	v_add_u32_e32 v62, s46, v4
	v_add_u32_e32 v63, s46, v5
	ds_read_b64 v[40:41], v62
	ds_read_b64 v[42:43], v63
	v_add_u32_e32 v62, s44, v6
	ds_read_b128 v[44:47], v62
	ds_read_b128 v[48:51], v62 offset:32
	s_add_i32 s42, s0, 1
	s_lshl_b32 s42, s42, 10
	s_add_i32 s42, s42, 0x12000
	s_add_u32 s6, s10, s42
	s_addc_u32 s7, s11, 0
	v_lshl_add_u64 v[8:9], v[0:1], 0, s[6:7]
	s_waitcnt lgkmcnt(6)
	v_lshlrev_b32_e32 v54, 16, v12
	v_and_b32_e32 v55, 0xffff0000, v12
	v_lshlrev_b32_e32 v56, 16, v13
	v_and_b32_e32 v57, 0xffff0000, v13
	v_lshlrev_b32_e32 v58, 16, v14
	v_and_b32_e32 v59, 0xffff0000, v14
	v_lshlrev_b32_e32 v60, 16, v15
	v_and_b32_e32 v61, 0xffff0000, v15
	v_pk_mul_f32 v[54:55], v[16:17], v[54:55] op_sel_hi:[0,1]
	v_pk_mul_f32 v[56:57], v[16:17], v[56:57] op_sel_hi:[0,1]
	v_pk_mul_f32 v[58:59], v[16:17], v[58:59] op_sel_hi:[0,1]
	v_pk_mul_f32 v[60:61], v[16:17], v[60:61] op_sel_hi:[0,1]
	v_cvt_pk_bf16_f32 v12, v54, v55
	v_cvt_pk_bf16_f32 v13, v56, v57
	v_cvt_pk_bf16_f32 v14, v58, v59
	v_cvt_pk_bf16_f32 v15, v60, v61
	global_store_dwordx4 v[8:9], v[12:15], off nt
	s_add_i32 s42, s0, 1
	s_lshr_b32 s43, s42, 2
	s_and_b32 s44, s42, 3
	s_lshl_b32 s46, s44, 1
	s_lshl_b32 s6, s43, 1
	s_xor_b32 s46, s46, s6
	s_lshl_b32 s46, s46, 4
	s_mul_i32 s43, s43, 0x1200
	s_add_i32 s46, s46, s43
	s_lshl_b32 s44, s44, 6
	s_addk_i32 s44, 0x700
	v_add_u32_e32 v62, s46, v4
	v_add_u32_e32 v63, s46, v5
	ds_read_b64 v[12:13], v62
	ds_read_b64 v[14:15], v63
	v_add_u32_e32 v62, s44, v6
	ds_read_b128 v[16:19], v62
	ds_read_b128 v[20:23], v62 offset:32
	s_add_i32 s42, s0, 2
	s_lshl_b32 s42, s42, 10
	s_add_i32 s42, s42, 0x12000
	s_add_u32 s6, s10, s42
	s_addc_u32 s7, s11, 0
	v_lshl_add_u64 v[8:9], v[0:1], 0, s[6:7]
	s_waitcnt lgkmcnt(8)
	v_lshlrev_b32_e32 v54, 16, v26
	v_and_b32_e32 v55, 0xffff0000, v26
	v_lshlrev_b32_e32 v56, 16, v27
	v_and_b32_e32 v57, 0xffff0000, v27
	v_lshlrev_b32_e32 v58, 16, v28
	v_and_b32_e32 v59, 0xffff0000, v28
	v_lshlrev_b32_e32 v60, 16, v29
	v_and_b32_e32 v61, 0xffff0000, v29
	v_pk_mul_f32 v[54:55], v[30:31], v[54:55] op_sel_hi:[0,1]
	v_pk_mul_f32 v[56:57], v[30:31], v[56:57] op_sel_hi:[0,1]
	v_pk_mul_f32 v[58:59], v[30:31], v[58:59] op_sel_hi:[0,1]
	v_pk_mul_f32 v[60:61], v[30:31], v[60:61] op_sel_hi:[0,1]
	v_cvt_pk_bf16_f32 v26, v54, v55
	v_cvt_pk_bf16_f32 v27, v56, v57
	v_cvt_pk_bf16_f32 v28, v58, v59
	v_cvt_pk_bf16_f32 v29, v60, v61
	global_store_dwordx4 v[8:9], v[26:29], off nt
	s_add_i32 s42, s0, 2
	s_lshr_b32 s43, s42, 2
	s_and_b32 s44, s42, 3
	s_lshl_b32 s46, s44, 1
	s_lshl_b32 s6, s43, 1
	s_xor_b32 s46, s46, s6
	s_lshl_b32 s46, s46, 4
	s_mul_i32 s43, s43, 0x1200
	s_add_i32 s46, s46, s43
	s_lshl_b32 s44, s44, 6
	s_addk_i32 s44, 0x700
	v_add_u32_e32 v62, s46, v4
	v_add_u32_e32 v63, s46, v5
	ds_read_b64 v[26:27], v62
	ds_read_b64 v[28:29], v63
	v_add_u32_e32 v62, s44, v6
	ds_read_b128 v[30:33], v62
	ds_read_b128 v[34:37], v62 offset:32
	s_add_i32 s42, s0, 0
	s_lshl_b32 s42, s42, 10
	s_add_i32 s42, s42, 0x12000
	s_add_u32 s6, s16, s42
	s_addc_u32 s7, s17, 0
	v_lshl_add_u64 v[8:9], v[0:1], 0, s[6:7]
	s_waitcnt lgkmcnt(8)
	v_lshlrev_b32_e32 v54, 16, v40
	v_and_b32_e32 v55, 0xffff0000, v40
	v_lshlrev_b32_e32 v56, 16, v41
	v_and_b32_e32 v57, 0xffff0000, v41
	v_lshlrev_b32_e32 v58, 16, v42
	v_and_b32_e32 v59, 0xffff0000, v42
	v_lshlrev_b32_e32 v60, 16, v43
	v_and_b32_e32 v61, 0xffff0000, v43
	v_pk_mul_f32 v[54:55], v[44:45], v[54:55]
	v_pk_mul_f32 v[56:57], v[46:47], v[56:57]
	v_pk_mul_f32 v[58:59], v[48:49], v[58:59]
	v_pk_mul_f32 v[60:61], v[50:51], v[60:61]
	v_cvt_pk_bf16_f32 v40, v54, v55
	v_cvt_pk_bf16_f32 v41, v56, v57
	v_cvt_pk_bf16_f32 v42, v58, v59
	v_cvt_pk_bf16_f32 v43, v60, v61
	global_store_dwordx4 v[8:9], v[40:43], off nt
	s_add_i32 s42, s1, 0
	s_lshr_b32 s43, s42, 2
	s_mul_i32 s46, s43, 0x1200
	s_and_b32 s44, s42, 3
	s_lshl_b32 s44, s44, 5
	s_add_i32 s46, s46, s44
	s_addk_i32 s46, 0x2400
	v_add_u32_e32 v62, s46, v7
	ds_read2_b64 v[40:43], v62 offset1:2
	s_add_i32 s42, s0, 1
	s_lshl_b32 s42, s42, 10
	s_add_i32 s42, s42, 0x12000
	s_add_u32 s6, s16, s42
	s_addc_u32 s7, s17, 0
	v_lshl_add_u64 v[8:9], v[0:1], 0, s[6:7]
	s_waitcnt lgkmcnt(5)
	v_lshlrev_b32_e32 v54, 16, v12
	v_and_b32_e32 v55, 0xffff0000, v12
	v_lshlrev_b32_e32 v56, 16, v13
	v_and_b32_e32 v57, 0xffff0000, v13
	v_lshlrev_b32_e32 v58, 16, v14
	v_and_b32_e32 v59, 0xffff0000, v14
	v_lshlrev_b32_e32 v60, 16, v15
	v_and_b32_e32 v61, 0xffff0000, v15
	v_pk_mul_f32 v[54:55], v[16:17], v[54:55]
	v_pk_mul_f32 v[56:57], v[18:19], v[56:57]
	v_pk_mul_f32 v[58:59], v[20:21], v[58:59]
	v_pk_mul_f32 v[60:61], v[22:23], v[60:61]
	v_cvt_pk_bf16_f32 v12, v54, v55
	v_cvt_pk_bf16_f32 v13, v56, v57
	v_cvt_pk_bf16_f32 v14, v58, v59
	v_cvt_pk_bf16_f32 v15, v60, v61
	global_store_dwordx4 v[8:9], v[12:15], off nt
	s_add_i32 s42, s1, 1
	s_lshr_b32 s43, s42, 2
	s_mul_i32 s46, s43, 0x1200
	s_and_b32 s44, s42, 3
	s_lshl_b32 s44, s44, 5
	s_add_i32 s46, s46, s44
	s_addk_i32 s46, 0x2400
	v_add_u32_e32 v62, s46, v7
	ds_read2_b64 v[12:15], v62 offset1:2
	s_add_i32 s42, s0, 2
	s_lshl_b32 s42, s42, 10
	s_add_i32 s42, s42, 0x12000
	s_add_u32 s6, s16, s42
	s_addc_u32 s7, s17, 0
	v_lshl_add_u64 v[8:9], v[0:1], 0, s[6:7]
	s_waitcnt lgkmcnt(2)
	v_lshlrev_b32_e32 v54, 16, v26
	v_and_b32_e32 v55, 0xffff0000, v26
	v_lshlrev_b32_e32 v56, 16, v27
	v_and_b32_e32 v57, 0xffff0000, v27
	v_lshlrev_b32_e32 v58, 16, v28
	v_and_b32_e32 v59, 0xffff0000, v28
	v_lshlrev_b32_e32 v60, 16, v29
	v_and_b32_e32 v61, 0xffff0000, v29
	v_pk_mul_f32 v[54:55], v[30:31], v[54:55]
	v_pk_mul_f32 v[56:57], v[32:33], v[56:57]
	v_pk_mul_f32 v[58:59], v[34:35], v[58:59]
	v_pk_mul_f32 v[60:61], v[36:37], v[60:61]
	v_cvt_pk_bf16_f32 v26, v54, v55
	v_cvt_pk_bf16_f32 v27, v56, v57
	v_cvt_pk_bf16_f32 v28, v58, v59
	v_cvt_pk_bf16_f32 v29, v60, v61
	global_store_dwordx4 v[8:9], v[26:29], off nt
	s_add_i32 s42, s1, 0
	s_lshl_b32 s42, s42, 10
	s_add_i32 s42, s42, 0x12000
	s_add_u32 s6, s26, s42
	s_addc_u32 s7, s27, 0
	v_lshl_add_u64 v[8:9], v[0:1], 0, s[6:7]
	s_waitcnt lgkmcnt(1)
	global_store_dwordx4 v[8:9], v[40:43], off nt
	s_add_i32 s42, s1, 1
	s_lshl_b32 s42, s42, 10
	s_add_i32 s42, s42, 0x12000
	s_add_u32 s6, s26, s42
	s_addc_u32 s7, s27, 0
	v_lshl_add_u64 v[8:9], v[0:1], 0, s[6:7]
	s_waitcnt lgkmcnt(0)
	global_store_dwordx4 v[8:9], v[12:15], off nt
	s_branch .Lf1_done
.Lf1_clsB:
	s_sub_u32 s0, s0, 4
	s_lshl_b32 s0, s0, 1
	s_add_i32 s0, s0, 12
	s_add_i32 s42, s0, 0
	s_lshr_b32 s43, s42, 3
	s_mul_i32 s46, s43, 0x2200
	s_and_b32 s44, s42, 7
	s_lshl_b32 s44, s44, 5
	s_add_i32 s46, s46, s44
	s_lshl_b32 s43, s43, 7
	s_addk_i32 s43, 0x400
	v_add_u32_e32 v62, s46, v2
	v_add_u32_e32 v63, s43, v3
	ds_read2_b64 v[12:15], v62 offset1:2
	ds_read_b32 v16, v63
	s_add_i32 s42, s0, 1
	s_lshr_b32 s43, s42, 3
	s_mul_i32 s46, s43, 0x2200
	s_and_b32 s44, s42, 7
	s_lshl_b32 s44, s44, 5
	s_add_i32 s46, s46, s44
	s_lshl_b32 s43, s43, 7
	s_addk_i32 s43, 0x400
	v_add_u32_e32 v62, s46, v2
	v_add_u32_e32 v63, s43, v3
	ds_read2_b64 v[26:29], v62 offset1:2
	ds_read_b32 v30, v63
	s_add_i32 s42, s0, 0
	s_lshr_b32 s43, s42, 2
	s_and_b32 s44, s42, 3
	s_lshl_b32 s46, s44, 1
	s_lshl_b32 s6, s43, 1
	s_xor_b32 s46, s46, s6
	s_lshl_b32 s46, s46, 4
	s_mul_i32 s43, s43, 0x1200
	s_add_i32 s46, s46, s43
	s_lshl_b32 s44, s44, 6
	s_addk_i32 s44, 0x600
	v_add_u32_e32 v62, s46, v4
	v_add_u32_e32 v63, s46, v5
	ds_read_b64 v[40:41], v62
	ds_read_b64 v[42:43], v63
	v_add_u32_e32 v62, s44, v6
	ds_read_b128 v[44:47], v62
	ds_read_b128 v[48:51], v62 offset:32
	s_add_i32 s42, s0, 0
	s_lshl_b32 s42, s42, 10
	s_add_u32 s6, s10, s42
	s_addc_u32 s7, s11, 0
	v_lshl_add_u64 v[8:9], v[0:1], 0, s[6:7]
	s_waitcnt lgkmcnt(6)
	v_lshlrev_b32_e32 v54, 16, v12
	v_and_b32_e32 v55, 0xffff0000, v12
	v_lshlrev_b32_e32 v56, 16, v13
	v_and_b32_e32 v57, 0xffff0000, v13
	v_lshlrev_b32_e32 v58, 16, v14
	v_and_b32_e32 v59, 0xffff0000, v14
	v_lshlrev_b32_e32 v60, 16, v15
	v_and_b32_e32 v61, 0xffff0000, v15
	v_pk_mul_f32 v[54:55], v[16:17], v[54:55] op_sel_hi:[0,1]
	v_pk_mul_f32 v[56:57], v[16:17], v[56:57] op_sel_hi:[0,1]
	v_pk_mul_f32 v[58:59], v[16:17], v[58:59] op_sel_hi:[0,1]
	v_pk_mul_f32 v[60:61], v[16:17], v[60:61] op_sel_hi:[0,1]
	v_cvt_pk_bf16_f32 v12, v54, v55
	v_cvt_pk_bf16_f32 v13, v56, v57
	v_cvt_pk_bf16_f32 v14, v58, v59
	v_cvt_pk_bf16_f32 v15, v60, v61
	global_store_dwordx4 v[8:9], v[12:15], off nt
	s_add_i32 s42, s0, 1
	s_lshr_b32 s43, s42, 2
	s_and_b32 s44, s42, 3
	s_lshl_b32 s46, s44, 1
	s_lshl_b32 s6, s43, 1
	s_xor_b32 s46, s46, s6
	s_lshl_b32 s46, s46, 4
	s_mul_i32 s43, s43, 0x1200
	s_add_i32 s46, s46, s43
	s_lshl_b32 s44, s44, 6
	s_addk_i32 s44, 0x600
	v_add_u32_e32 v62, s46, v4
	v_add_u32_e32 v63, s46, v5
	ds_read_b64 v[12:13], v62
	ds_read_b64 v[14:15], v63
	v_add_u32_e32 v62, s44, v6
	ds_read_b128 v[16:19], v62
	ds_read_b128 v[20:23], v62 offset:32
	s_add_i32 s42, s0, 1
	s_lshl_b32 s42, s42, 10
	s_add_u32 s6, s10, s42
	s_addc_u32 s7, s11, 0
	v_lshl_add_u64 v[8:9], v[0:1], 0, s[6:7]
	s_waitcnt lgkmcnt(8)
	v_lshlrev_b32_e32 v54, 16, v26
	v_and_b32_e32 v55, 0xffff0000, v26
	v_lshlrev_b32_e32 v56, 16, v27
	v_and_b32_e32 v57, 0xffff0000, v27
	v_lshlrev_b32_e32 v58, 16, v28
	v_and_b32_e32 v59, 0xffff0000, v28
	v_lshlrev_b32_e32 v60, 16, v29
	v_and_b32_e32 v61, 0xffff0000, v29
	v_pk_mul_f32 v[54:55], v[30:31], v[54:55] op_sel_hi:[0,1]
	v_pk_mul_f32 v[56:57], v[30:31], v[56:57] op_sel_hi:[0,1]
	v_pk_mul_f32 v[58:59], v[30:31], v[58:59] op_sel_hi:[0,1]
	v_pk_mul_f32 v[60:61], v[30:31], v[60:61] op_sel_hi:[0,1]
	v_cvt_pk_bf16_f32 v26, v54, v55
	v_cvt_pk_bf16_f32 v27, v56, v57
	v_cvt_pk_bf16_f32 v28, v58, v59
	v_cvt_pk_bf16_f32 v29, v60, v61
	global_store_dwordx4 v[8:9], v[26:29], off nt
	s_add_i32 s42, s0, 0
	s_lshr_b32 s43, s42, 3
	s_mul_i32 s46, s43, 0x2200
	s_and_b32 s44, s42, 7
	s_lshl_b32 s44, s44, 5
	s_add_i32 s46, s46, s44
	s_lshl_b32 s43, s43, 7
	s_addk_i32 s43, 0x500
	v_add_u32_e32 v62, s46, v2
	v_add_u32_e32 v63, s43, v3
	ds_read2_b64 v[26:29], v62 offset1:2
	ds_read_b32 v30, v63
	s_add_i32 s42, s0, 0
	s_lshl_b32 s42, s42, 10
	s_add_u32 s6, s16, s42
	s_addc_u32 s7, s17, 0
	v_lshl_add_u64 v[8:9], v[0:1], 0, s[6:7]
	s_waitcnt lgkmcnt(6)
	v_lshlrev_b32_e32 v54, 16, v40
	v_and_b32_e32 v55, 0xffff0000, v40
	v_lshlrev_b32_e32 v56, 16, v41
	v_and_b32_e32 v57, 0xffff0000, v41
	v_lshlrev_b32_e32 v58, 16, v42
	v_and_b32_e32 v59, 0xffff0000, v42
	v_lshlrev_b32_e32 v60, 16, v43
	v_and_b32_e32 v61, 0xffff0000, v43
	v_pk_mul_f32 v[54:55], v[44:45], v[54:55]
	v_pk_mul_f32 v[56:57], v[46:47], v[56:57]
	v_pk_mul_f32 v[58:59], v[48:49], v[58:59]
	v_pk_mul_f32 v[60:61], v[50:51], v[60:61]
	v_cvt_pk_bf16_f32 v40, v54, v55
	v_cvt_pk_bf16_f32 v41, v56, v57
	v_cvt_pk_bf16_f32 v42, v58, v59
	v_cvt_pk_bf16_f32 v43, v60, v61
	global_store_dwordx4 v[8:9], v[40:43], off nt
	s_add_i32 s42, s0, 1
	s_lshr_b32 s43, s42, 3
	s_mul_i32 s46, s43, 0x2200
	s_and_b32 s44, s42, 7
	s_lshl_b32 s44, s44, 5
	s_add_i32 s46, s46, s44
	s_lshl_b32 s43, s43, 7
	s_addk_i32 s43, 0x500
	v_add_u32_e32 v62, s46, v2
	v_add_u32_e32 v63, s43, v3
	ds_read2_b64 v[40:43], v62 offset1:2
	ds_read_b32 v44, v63
	s_add_i32 s42, s0, 1
	s_lshl_b32 s42, s42, 10
	s_add_u32 s6, s16, s42
	s_addc_u32 s7, s17, 0
	v_lshl_add_u64 v[8:9], v[0:1], 0, s[6:7]
	s_waitcnt lgkmcnt(4)
	v_lshlrev_b32_e32 v54, 16, v12
	v_and_b32_e32 v55, 0xffff0000, v12
	v_lshlrev_b32_e32 v56, 16, v13
	v_and_b32_e32 v57, 0xffff0000, v13
	v_lshlrev_b32_e32 v58, 16, v14
	v_and_b32_e32 v59, 0xffff0000, v14
	v_lshlrev_b32_e32 v60, 16, v15
	v_and_b32_e32 v61, 0xffff0000, v15
	v_pk_mul_f32 v[54:55], v[16:17], v[54:55]
	v_pk_mul_f32 v[56:57], v[18:19], v[56:57]
	v_pk_mul_f32 v[58:59], v[20:21], v[58:59]
	v_pk_mul_f32 v[60:61], v[22:23], v[60:61]
	v_cvt_pk_bf16_f32 v12, v54, v55
	v_cvt_pk_bf16_f32 v13, v56, v57
	v_cvt_pk_bf16_f32 v14, v58, v59
	v_cvt_pk_bf16_f32 v15, v60, v61
	global_store_dwordx4 v[8:9], v[12:15], off nt
	s_add_i32 s42, s0, 0
	s_lshr_b32 s43, s42, 2
	s_and_b32 s44, s42, 3
	s_lshl_b32 s46, s44, 1
	s_lshl_b32 s6, s43, 1
	s_xor_b32 s46, s46, s6
	s_lshl_b32 s46, s46, 4
	s_mul_i32 s43, s43, 0x1200
	s_add_i32 s46, s46, s43
	s_lshl_b32 s44, s44, 6
	s_addk_i32 s44, 0x700
	v_add_u32_e32 v62, s46, v4
	v_add_u32_e32 v63, s46, v5
	ds_read_b64 v[12:13], v62
	ds_read_b64 v[14:15], v63
	v_add_u32_e32 v62, s44, v6
	ds_read_b128 v[16:19], v62
	ds_read_b128 v[20:23], v62 offset:32
	s_add_i32 s42, s0, 0
	s_lshl_b32 s42, s42, 10
	s_add_i32 s42, s42, 0x12000
	s_add_u32 s6, s10, s42
	s_addc_u32 s7, s11, 0
	v_lshl_add_u64 v[8:9], v[0:1], 0, s[6:7]
	s_waitcnt lgkmcnt(6)
	v_lshlrev_b32_e32 v54, 16, v26
	v_and_b32_e32 v55, 0xffff0000, v26
	v_lshlrev_b32_e32 v56, 16, v27
	v_and_b32_e32 v57, 0xffff0000, v27
	v_lshlrev_b32_e32 v58, 16, v28
	v_and_b32_e32 v59, 0xffff0000, v28
	v_lshlrev_b32_e32 v60, 16, v29
	v_and_b32_e32 v61, 0xffff0000, v29
	v_pk_mul_f32 v[54:55], v[30:31], v[54:55] op_sel_hi:[0,1]
	v_pk_mul_f32 v[56:57], v[30:31], v[56:57] op_sel_hi:[0,1]
	v_pk_mul_f32 v[58:59], v[30:31], v[58:59] op_sel_hi:[0,1]
	v_pk_mul_f32 v[60:61], v[30:31], v[60:61] op_sel_hi:[0,1]
	v_cvt_pk_bf16_f32 v26, v54, v55
	v_cvt_pk_bf16_f32 v27, v56, v57
	v_cvt_pk_bf16_f32 v28, v58, v59
	v_cvt_pk_bf16_f32 v29, v60, v61
	global_store_dwordx4 v[8:9], v[26:29], off nt
	s_add_i32 s42, s0, 1
	s_lshr_b32 s43, s42, 2
	s_and_b32 s44, s42, 3
	s_lshl_b32 s46, s44, 1
	s_lshl_b32 s6, s43, 1
	s_xor_b32 s46, s46, s6
	s_lshl_b32 s46, s46, 4
	s_mul_i32 s43, s43, 0x1200
	s_add_i32 s46, s46, s43
	s_lshl_b32 s44, s44, 6
	s_addk_i32 s44, 0x700
	v_add_u32_e32 v62, s46, v4
	v_add_u32_e32 v63, s46, v5
	ds_read_b64 v[26:27], v62
	ds_read_b64 v[28:29], v63
	v_add_u32_e32 v62, s44, v6
	ds_read_b128 v[30:33], v62
	ds_read_b128 v[34:37], v62 offset:32
	s_add_i32 s42, s0, 1
	s_lshl_b32 s42, s42, 10
	s_add_i32 s42, s42, 0x12000
	s_add_u32 s6, s10, s42
	s_addc_u32 s7, s11, 0
	v_lshl_add_u64 v[8:9], v[0:1], 0, s[6:7]
	s_waitcnt lgkmcnt(8)
	v_lshlrev_b32_e32 v54, 16, v40
	v_and_b32_e32 v55, 0xffff0000, v40
	v_lshlrev_b32_e32 v56, 16, v41
	v_and_b32_e32 v57, 0xffff0000, v41
	v_lshlrev_b32_e32 v58, 16, v42
	v_and_b32_e32 v59, 0xffff0000, v42
	v_lshlrev_b32_e32 v60, 16, v43
	v_and_b32_e32 v61, 0xffff0000, v43
	v_pk_mul_f32 v[54:55], v[44:45], v[54:55] op_sel_hi:[0,1]
	v_pk_mul_f32 v[56:57], v[44:45], v[56:57] op_sel_hi:[0,1]
	v_pk_mul_f32 v[58:59], v[44:45], v[58:59] op_sel_hi:[0,1]
	v_pk_mul_f32 v[60:61], v[44:45], v[60:61] op_sel_hi:[0,1]
	v_cvt_pk_bf16_f32 v40, v54, v55
	v_cvt_pk_bf16_f32 v41, v56, v57
	v_cvt_pk_bf16_f32 v42, v58, v59
	v_cvt_pk_bf16_f32 v43, v60, v61
	global_store_dwordx4 v[8:9], v[40:43], off nt
	s_add_i32 s42, s0, 0
	s_lshl_b32 s42, s42, 10
	s_add_i32 s42, s42, 0x12000
	s_add_u32 s6, s16, s42
	s_addc_u32 s7, s17, 0
	v_lshl_add_u64 v[8:9], v[0:1], 0, s[6:7]
	s_waitcnt lgkmcnt(4)
	v_lshlrev_b32_e32 v54, 16, v12
	v_and_b32_e32 v55, 0xffff0000, v12
	v_lshlrev_b32_e32 v56, 16, v13
	v_and_b32_e32 v57, 0xffff0000, v13
	v_lshlrev_b32_e32 v58, 16, v14
	v_and_b32_e32 v59, 0xffff0000, v14
	v_lshlrev_b32_e32 v60, 16, v15
	v_and_b32_e32 v61, 0xffff0000, v15
	v_pk_mul_f32 v[54:55], v[16:17], v[54:55]
	v_pk_mul_f32 v[56:57], v[18:19], v[56:57]
	v_pk_mul_f32 v[58:59], v[20:21], v[58:59]
	v_pk_mul_f32 v[60:61], v[22:23], v[60:61]
	v_cvt_pk_bf16_f32 v12, v54, v55
	v_cvt_pk_bf16_f32 v13, v56, v57
	v_cvt_pk_bf16_f32 v14, v58, v59
	v_cvt_pk_bf16_f32 v15, v60, v61
	global_store_dwordx4 v[8:9], v[12:15], off nt
	s_add_i32 s42, s0, 1
	s_lshl_b32 s42, s42, 10
	s_add_i32 s42, s42, 0x12000
	s_add_u32 s6, s16, s42
	s_addc_u32 s7, s17, 0
	v_lshl_add_u64 v[8:9], v[0:1], 0, s[6:7]
	s_waitcnt lgkmcnt(0)
	v_lshlrev_b32_e32 v54, 16, v26
	v_and_b32_e32 v55, 0xffff0000, v26
	v_lshlrev_b32_e32 v56, 16, v27
	v_and_b32_e32 v57, 0xffff0000, v27
	v_lshlrev_b32_e32 v58, 16, v28
	v_and_b32_e32 v59, 0xffff0000, v28
	v_lshlrev_b32_e32 v60, 16, v29
	v_and_b32_e32 v61, 0xffff0000, v29
	v_pk_mul_f32 v[54:55], v[30:31], v[54:55]
	v_pk_mul_f32 v[56:57], v[32:33], v[56:57]
	v_pk_mul_f32 v[58:59], v[34:35], v[58:59]
	v_pk_mul_f32 v[60:61], v[36:37], v[60:61]
	v_cvt_pk_bf16_f32 v26, v54, v55
	v_cvt_pk_bf16_f32 v27, v56, v57
	v_cvt_pk_bf16_f32 v28, v58, v59
	v_cvt_pk_bf16_f32 v29, v60, v61
	global_store_dwordx4 v[8:9], v[26:29], off nt
.Lf1_done:
.LBB0_281:
.LBB0_282:
	s_andn2_saveexec_b64 s[44:45], s[2:3]
	s_cbranch_execz .LBB0_296
	v_cndmask_b32_e64 v194, v244, v245, s[38:39]
	v_mov_b32_e32 v200, 0
	v_mov_b32_e32 v201, 0
	v_mov_b32_e32 v203, 0
	v_mul_u32_u24_e32 v204, 0x2280, v189
	v_add_u32_e32 v195, v194, v204
	v_mul_u32_u24_e32 v204, 0x1100, v189
	v_add_u32_e32 v204, 0x2200, v204
	v_add_u32_e32 v196, v194, v204
	s_cmp_lg_u32 s87, 0
	s_cselect_b32 s0, 0x2000, 0
	s_add_u32 s0, s0, 0x1e800
	v_lshlrev_b32_e32 v199, 2, v188
	v_lshl_add_u32 v197, v189, 11, s0
	v_sub_u32_e32 v204, 1, v189
	v_lshl_add_u32 v204, v204, 12, s0
	v_add_u32_e32 v198, v204, v199
	ds_read_b128 v[80:83], v195 offset:272
	v_cmp_eq_u32_e32 vcc, 0, v188
	s_nop 1
	v_cndmask_b32_e64 v0, 0, 1.0, vcc
	v_cmp_eq_u32_e32 vcc, 1, v188
	s_nop 1
	v_cndmask_b32_e64 v202, 0, 1.0, vcc
	s_waitcnt lgkmcnt(0)
	v_fma_f32 v146, -v0, v80, v202
	ds_read_b128 v[80:83], v195 offset:544
	v_mov_b32_e32 v1, v146
	v_cmp_eq_u32_e32 vcc, 2, v188
	s_nop 1
	v_cndmask_b32_e64 v202, 0, 1.0, vcc
	s_waitcnt lgkmcnt(0)
	v_pk_fma_f32 v[146:147], v[0:1], v[80:81], v[202:203] neg_lo:[1,0,0] neg_hi:[1,0,0]
	ds_read_b128 v[80:83], v195 offset:816
	v_add_f32_e32 v2, v146, v147
	v_cmp_eq_u32_e32 vcc, 3, v188
	s_nop 1
	v_cndmask_b32_e64 v202, 0, 1.0, vcc
	s_waitcnt lgkmcnt(0)
	v_pk_fma_f32 v[146:147], v[0:1], v[80:81], v[202:203] neg_lo:[1,0,0] neg_hi:[1,0,0]
	v_fma_f32 v148, -v2, v82, v200
	ds_read_b128 v[80:83], v195 offset:1088
	v_add_f32_e32 v150, v146, v147
	v_add_f32_e32 v3, v148, v150
	v_cmp_eq_u32_e32 vcc, 4, v188
	s_nop 1
	v_cndmask_b32_e64 v202, 0, 1.0, vcc
	s_waitcnt lgkmcnt(0)
	v_pk_fma_f32 v[146:147], v[0:1], v[80:81], v[202:203] neg_lo:[1,0,0] neg_hi:[1,0,0]
	v_pk_fma_f32 v[148:149], v[2:3], v[82:83], v[200:201] neg_lo:[1,0,0] neg_hi:[1,0,0]
	ds_read_b128 v[80:83], v195 offset:1360
	ds_read_b128 v[84:87], v195 offset:1376
	v_add_f32_e32 v150, v147, v146
	v_add_f32_e32 v151, v148, v149
	v_add_f32_e32 v4, v151, v150
	v_cmp_eq_u32_e32 vcc, 5, v188
	s_nop 1
	v_cndmask_b32_e64 v202, 0, 1.0, vcc
	s_waitcnt lgkmcnt(0)
	v_pk_fma_f32 v[146:147], v[0:1], v[80:81], v[202:203] neg_lo:[1,0,0] neg_hi:[1,0,0]
	v_pk_fma_f32 v[148:149], v[2:3], v[82:83], v[200:201] neg_lo:[1,0,0] neg_hi:[1,0,0]
	ds_read_b128 v[80:83], v195 offset:1632
	v_fma_f32 v146, -v4, v84, v146
	ds_read_b128 v[84:87], v195 offset:1648
	v_add_f32_e32 v150, v147, v146
	v_add_f32_e32 v151, v148, v149
	v_add_f32_e32 v5, v151, v150
	v_cmp_eq_u32_e32 vcc, 6, v188
	s_nop 1
	v_cndmask_b32_e64 v202, 0, 1.0, vcc
	s_waitcnt lgkmcnt(0)
	v_pk_fma_f32 v[146:147], v[0:1], v[80:81], v[202:203] neg_lo:[1,0,0] neg_hi:[1,0,0]
	v_pk_fma_f32 v[148:149], v[2:3], v[82:83], v[200:201] neg_lo:[1,0,0] neg_hi:[1,0,0]
	ds_read_b128 v[80:83], v195 offset:1904
	v_pk_fma_f32 v[146:147], v[4:5], v[84:85], v[146:147] neg_lo:[1,0,0] neg_hi:[1,0,0]
	ds_read_b128 v[84:87], v195 offset:1920
	v_add_f32_e32 v150, v147, v146
	v_add_f32_e32 v151, v148, v149
	v_add_f32_e32 v6, v151, v150
	v_cmp_eq_u32_e32 vcc, 7, v188
	s_nop 1
	v_cndmask_b32_e64 v202, 0, 1.0, vcc
	s_waitcnt lgkmcnt(0)
	v_pk_fma_f32 v[146:147], v[0:1], v[80:81], v[202:203] neg_lo:[1,0,0] neg_hi:[1,0,0]
	v_pk_fma_f32 v[148:149], v[2:3], v[82:83], v[200:201] neg_lo:[1,0,0] neg_hi:[1,0,0]
	ds_read_b128 v[80:83], v195 offset:2176
	v_pk_fma_f32 v[146:147], v[4:5], v[84:85], v[146:147] neg_lo:[1,0,0] neg_hi:[1,0,0]
	v_fma_f32 v148, -v6, v86, v148
	ds_read_b128 v[84:87], v195 offset:2192
	v_add_f32_e32 v150, v147, v146
	v_add_f32_e32 v151, v148, v149
	v_add_f32_e32 v7, v151, v150
	v_cmp_eq_u32_e32 vcc, 8, v188
	s_nop 1
	v_cndmask_b32_e64 v202, 0, 1.0, vcc
	s_waitcnt lgkmcnt(0)
	v_pk_fma_f32 v[146:147], v[0:1], v[80:81], v[202:203] neg_lo:[1,0,0] neg_hi:[1,0,0]
	v_pk_fma_f32 v[148:149], v[2:3], v[82:83], v[200:201] neg_lo:[1,0,0] neg_hi:[1,0,0]
	ds_read_b128 v[80:83], v195 offset:2448
	v_pk_fma_f32 v[146:147], v[4:5], v[84:85], v[146:147] neg_lo:[1,0,0] neg_hi:[1,0,0]
	v_pk_fma_f32 v[148:149], v[6:7], v[86:87], v[148:149] neg_lo:[1,0,0] neg_hi:[1,0,0]
	ds_read_b128 v[84:87], v195 offset:2464
	ds_read_b128 v[88:91], v195 offset:2480
	v_add_f32_e32 v150, v147, v146
	v_add_f32_e32 v151, v148, v149
	v_add_f32_e32 v8, v151, v150
	v_cmp_eq_u32_e32 vcc, 9, v188
	s_nop 1
	v_cndmask_b32_e64 v202, 0, 1.0, vcc
	s_waitcnt lgkmcnt(0)
	v_pk_fma_f32 v[146:147], v[0:1], v[80:81], v[202:203] neg_lo:[1,0,0] neg_hi:[1,0,0]
	v_pk_fma_f32 v[148:149], v[2:3], v[82:83], v[200:201] neg_lo:[1,0,0] neg_hi:[1,0,0]
	ds_read_b128 v[80:83], v195 offset:2720
	v_pk_fma_f32 v[146:147], v[4:5], v[84:85], v[146:147] neg_lo:[1,0,0] neg_hi:[1,0,0]
	v_pk_fma_f32 v[148:149], v[6:7], v[86:87], v[148:149] neg_lo:[1,0,0] neg_hi:[1,0,0]
	ds_read_b128 v[84:87], v195 offset:2736
	v_fma_f32 v146, -v8, v88, v146
	ds_read_b128 v[88:91], v195 offset:2752
	v_add_f32_e32 v150, v147, v146
	v_add_f32_e32 v151, v148, v149
	v_add_f32_e32 v9, v151, v150
	v_cmp_eq_u32_e32 vcc, 10, v188
	s_nop 1
	v_cndmask_b32_e64 v202, 0, 1.0, vcc
	s_waitcnt lgkmcnt(0)
	v_pk_fma_f32 v[146:147], v[0:1], v[80:81], v[202:203] neg_lo:[1,0,0] neg_hi:[1,0,0]
	v_pk_fma_f32 v[148:149], v[2:3], v[82:83], v[200:201] neg_lo:[1,0,0] neg_hi:[1,0,0]
	ds_read_b128 v[80:83], v195 offset:2992
	v_pk_fma_f32 v[146:147], v[4:5], v[84:85], v[146:147] neg_lo:[1,0,0] neg_hi:[1,0,0]
	v_pk_fma_f32 v[148:149], v[6:7], v[86:87], v[148:149] neg_lo:[1,0,0] neg_hi:[1,0,0]
	ds_read_b128 v[84:87], v195 offset:3008
	v_pk_fma_f32 v[146:147], v[8:9], v[88:89], v[146:147] neg_lo:[1,0,0] neg_hi:[1,0,0]
	ds_read_b128 v[88:91], v195 offset:3024
	v_add_f32_e32 v150, v147, v146
	v_add_f32_e32 v151, v148, v149
	v_add_f32_e32 v10, v151, v150
	v_cmp_eq_u32_e32 vcc, 11, v188
	s_nop 1
	v_cndmask_b32_e64 v202, 0, 1.0, vcc
	s_waitcnt lgkmcnt(0)
	v_pk_fma_f32 v[146:147], v[0:1], v[80:81], v[202:203] neg_lo:[1,0,0] neg_hi:[1,0,0]
	v_pk_fma_f32 v[148:149], v[2:3], v[82:83], v[200:201] neg_lo:[1,0,0] neg_hi:[1,0,0]
	ds_read_b128 v[80:83], v195 offset:3264
	v_pk_fma_f32 v[146:147], v[4:5], v[84:85], v[146:147] neg_lo:[1,0,0] neg_hi:[1,0,0]
	v_pk_fma_f32 v[148:149], v[6:7], v[86:87], v[148:149] neg_lo:[1,0,0] neg_hi:[1,0,0]
	ds_read_b128 v[84:87], v195 offset:3280
	v_pk_fma_f32 v[146:147], v[8:9], v[88:89], v[146:147] neg_lo:[1,0,0] neg_hi:[1,0,0]
	v_fma_f32 v148, -v10, v90, v148
	ds_read_b128 v[88:91], v195 offset:3296
	v_add_f32_e32 v150, v147, v146
	v_add_f32_e32 v151, v148, v149
	v_add_f32_e32 v11, v151, v150
	v_cmp_eq_u32_e32 vcc, 12, v188
	s_nop 1
	v_cndmask_b32_e64 v202, 0, 1.0, vcc
	s_waitcnt lgkmcnt(0)
	v_pk_fma_f32 v[146:147], v[0:1], v[80:81], v[202:203] neg_lo:[1,0,0] neg_hi:[1,0,0]
	v_pk_fma_f32 v[148:149], v[2:3], v[82:83], v[200:201] neg_lo:[1,0,0] neg_hi:[1,0,0]
	ds_read_b128 v[80:83], v195 offset:3536
	v_pk_fma_f32 v[146:147], v[4:5], v[84:85], v[146:147] neg_lo:[1,0,0] neg_hi:[1,0,0]
	v_pk_fma_f32 v[148:149], v[6:7], v[86:87], v[148:149] neg_lo:[1,0,0] neg_hi:[1,0,0]
	ds_read_b128 v[84:87], v195 offset:3552
	v_pk_fma_f32 v[146:147], v[8:9], v[88:89], v[146:147] neg_lo:[1,0,0] neg_hi:[1,0,0]
	v_pk_fma_f32 v[148:149], v[10:11], v[90:91], v[148:149] neg_lo:[1,0,0] neg_hi:[1,0,0]
	ds_read_b128 v[88:91], v195 offset:3568
	ds_read_b128 v[92:95], v195 offset:3584
	v_add_f32_e32 v150, v147, v146
	v_add_f32_e32 v151, v148, v149
	v_add_f32_e32 v12, v151, v150
	v_cmp_eq_u32_e32 vcc, 13, v188
	s_nop 1
	v_cndmask_b32_e64 v202, 0, 1.0, vcc
	s_waitcnt lgkmcnt(0)
	v_pk_fma_f32 v[146:147], v[0:1], v[80:81], v[202:203] neg_lo:[1,0,0] neg_hi:[1,0,0]
	v_pk_fma_f32 v[148:149], v[2:3], v[82:83], v[200:201] neg_lo:[1,0,0] neg_hi:[1,0,0]
	ds_read_b128 v[80:83], v195 offset:3808
	v_pk_fma_f32 v[146:147], v[4:5], v[84:85], v[146:147] neg_lo:[1,0,0] neg_hi:[1,0,0]
	v_pk_fma_f32 v[148:149], v[6:7], v[86:87], v[148:149] neg_lo:[1,0,0] neg_hi:[1,0,0]
	ds_read_b128 v[84:87], v195 offset:3824
	v_pk_fma_f32 v[146:147], v[8:9], v[88:89], v[146:147] neg_lo:[1,0,0] neg_hi:[1,0,0]
	v_pk_fma_f32 v[148:149], v[10:11], v[90:91], v[148:149] neg_lo:[1,0,0] neg_hi:[1,0,0]
	ds_read_b128 v[88:91], v195 offset:3840
	v_fma_f32 v146, -v12, v92, v146
	ds_read_b128 v[92:95], v195 offset:3856
	v_add_f32_e32 v150, v147, v146
	v_add_f32_e32 v151, v148, v149
	v_add_f32_e32 v13, v151, v150
	v_cmp_eq_u32_e32 vcc, 14, v188
	s_nop 1
	v_cndmask_b32_e64 v202, 0, 1.0, vcc
	s_waitcnt lgkmcnt(0)
	v_pk_fma_f32 v[146:147], v[0:1], v[80:81], v[202:203] neg_lo:[1,0,0] neg_hi:[1,0,0]
	v_pk_fma_f32 v[148:149], v[2:3], v[82:83], v[200:201] neg_lo:[1,0,0] neg_hi:[1,0,0]
	ds_read_b128 v[80:83], v195 offset:4080
	v_pk_fma_f32 v[146:147], v[4:5], v[84:85], v[146:147] neg_lo:[1,0,0] neg_hi:[1,0,0]
	v_pk_fma_f32 v[148:149], v[6:7], v[86:87], v[148:149] neg_lo:[1,0,0] neg_hi:[1,0,0]
	ds_read_b128 v[84:87], v195 offset:4096
	v_pk_fma_f32 v[146:147], v[8:9], v[88:89], v[146:147] neg_lo:[1,0,0] neg_hi:[1,0,0]
	v_pk_fma_f32 v[148:149], v[10:11], v[90:91], v[148:149] neg_lo:[1,0,0] neg_hi:[1,0,0]
	ds_read_b128 v[88:91], v195 offset:4112
	v_pk_fma_f32 v[146:147], v[12:13], v[92:93], v[146:147] neg_lo:[1,0,0] neg_hi:[1,0,0]
	ds_read_b128 v[92:95], v195 offset:4128
	v_add_f32_e32 v150, v147, v146
	v_add_f32_e32 v151, v148, v149
	v_add_f32_e32 v14, v151, v150
	v_cmp_eq_u32_e32 vcc, 15, v188
	s_nop 1
	v_cndmask_b32_e64 v202, 0, 1.0, vcc
	s_waitcnt lgkmcnt(0)
	v_pk_fma_f32 v[146:147], v[0:1], v[80:81], v[202:203] neg_lo:[1,0,0] neg_hi:[1,0,0]
	v_pk_fma_f32 v[148:149], v[2:3], v[82:83], v[200:201] neg_lo:[1,0,0] neg_hi:[1,0,0]
	ds_read_b128 v[80:83], v195 offset:4352
	v_pk_fma_f32 v[146:147], v[4:5], v[84:85], v[146:147] neg_lo:[1,0,0] neg_hi:[1,0,0]
	v_pk_fma_f32 v[148:149], v[6:7], v[86:87], v[148:149] neg_lo:[1,0,0] neg_hi:[1,0,0]
	ds_read_b128 v[84:87], v195 offset:4368
	v_pk_fma_f32 v[146:147], v[8:9], v[88:89], v[146:147] neg_lo:[1,0,0] neg_hi:[1,0,0]
	v_pk_fma_f32 v[148:149], v[10:11], v[90:91], v[148:149] neg_lo:[1,0,0] neg_hi:[1,0,0]
	ds_read_b128 v[88:91], v195 offset:4384
	v_pk_fma_f32 v[146:147], v[12:13], v[92:93], v[146:147] neg_lo:[1,0,0] neg_hi:[1,0,0]
	v_fma_f32 v148, -v14, v94, v148
	ds_read_b128 v[92:95], v195 offset:4400
	v_add_f32_e32 v150, v147, v146
	v_add_f32_e32 v151, v148, v149
	v_add_f32_e32 v15, v151, v150
	v_cmp_eq_u32_e32 vcc, 16, v188
	s_nop 1
	v_cndmask_b32_e64 v202, 0, 1.0, vcc
	s_waitcnt lgkmcnt(0)
	v_pk_fma_f32 v[146:147], v[0:1], v[80:81], v[202:203] neg_lo:[1,0,0] neg_hi:[1,0,0]
	v_pk_fma_f32 v[148:149], v[2:3], v[82:83], v[200:201] neg_lo:[1,0,0] neg_hi:[1,0,0]
	ds_read_b128 v[80:83], v195 offset:4624
	v_pk_fma_f32 v[146:147], v[4:5], v[84:85], v[146:147] neg_lo:[1,0,0] neg_hi:[1,0,0]
	v_pk_fma_f32 v[148:149], v[6:7], v[86:87], v[148:149] neg_lo:[1,0,0] neg_hi:[1,0,0]
	ds_read_b128 v[84:87], v195 offset:4640
	v_pk_fma_f32 v[146:147], v[8:9], v[88:89], v[146:147] neg_lo:[1,0,0] neg_hi:[1,0,0]
	v_pk_fma_f32 v[148:149], v[10:11], v[90:91], v[148:149] neg_lo:[1,0,0] neg_hi:[1,0,0]
	ds_read_b128 v[88:91], v195 offset:4656
	v_pk_fma_f32 v[146:147], v[12:13], v[92:93], v[146:147] neg_lo:[1,0,0] neg_hi:[1,0,0]
	v_pk_fma_f32 v[148:149], v[14:15], v[94:95], v[148:149] neg_lo:[1,0,0] neg_hi:[1,0,0]
	ds_read_b128 v[92:95], v195 offset:4672
	ds_read_b128 v[96:99], v195 offset:4688
	v_add_f32_e32 v150, v147, v146
	v_add_f32_e32 v151, v148, v149
	v_add_f32_e32 v16, v151, v150
	v_cmp_eq_u32_e32 vcc, 17, v188
	s_nop 1
	v_cndmask_b32_e64 v202, 0, 1.0, vcc
	s_waitcnt lgkmcnt(1)
	v_pk_fma_f32 v[146:147], v[0:1], v[80:81], v[202:203] neg_lo:[1,0,0] neg_hi:[1,0,0]
	v_pk_fma_f32 v[148:149], v[2:3], v[82:83], v[200:201] neg_lo:[1,0,0] neg_hi:[1,0,0]
	ds_read_b128 v[80:83], v195 offset:4896
	v_pk_fma_f32 v[146:147], v[4:5], v[84:85], v[146:147] neg_lo:[1,0,0] neg_hi:[1,0,0]
	v_pk_fma_f32 v[148:149], v[6:7], v[86:87], v[148:149] neg_lo:[1,0,0] neg_hi:[1,0,0]
	ds_read_b128 v[84:87], v195 offset:4912
	v_pk_fma_f32 v[146:147], v[8:9], v[88:89], v[146:147] neg_lo:[1,0,0] neg_hi:[1,0,0]
	v_pk_fma_f32 v[148:149], v[10:11], v[90:91], v[148:149] neg_lo:[1,0,0] neg_hi:[1,0,0]
	ds_read_b128 v[88:91], v195 offset:4928
	v_pk_fma_f32 v[146:147], v[12:13], v[92:93], v[146:147] neg_lo:[1,0,0] neg_hi:[1,0,0]
	v_pk_fma_f32 v[148:149], v[14:15], v[94:95], v[148:149] neg_lo:[1,0,0] neg_hi:[1,0,0]
	ds_read_b128 v[92:95], v195 offset:4944
	s_waitcnt lgkmcnt(4)
	v_fma_f32 v146, -v16, v96, v146
	ds_read_b128 v[96:99], v195 offset:4960
	v_add_f32_e32 v150, v147, v146
	v_add_f32_e32 v151, v148, v149
	v_add_f32_e32 v17, v151, v150
	v_cmp_eq_u32_e32 vcc, 18, v188
	s_nop 1
	v_cndmask_b32_e64 v202, 0, 1.0, vcc
	s_waitcnt lgkmcnt(1)
	v_pk_fma_f32 v[146:147], v[0:1], v[80:81], v[202:203] neg_lo:[1,0,0] neg_hi:[1,0,0]
	v_pk_fma_f32 v[148:149], v[2:3], v[82:83], v[200:201] neg_lo:[1,0,0] neg_hi:[1,0,0]
	ds_read_b128 v[80:83], v195 offset:5168
	v_pk_fma_f32 v[146:147], v[4:5], v[84:85], v[146:147] neg_lo:[1,0,0] neg_hi:[1,0,0]
	v_pk_fma_f32 v[148:149], v[6:7], v[86:87], v[148:149] neg_lo:[1,0,0] neg_hi:[1,0,0]
	ds_read_b128 v[84:87], v195 offset:5184
	v_pk_fma_f32 v[146:147], v[8:9], v[88:89], v[146:147] neg_lo:[1,0,0] neg_hi:[1,0,0]
	v_pk_fma_f32 v[148:149], v[10:11], v[90:91], v[148:149] neg_lo:[1,0,0] neg_hi:[1,0,0]
	ds_read_b128 v[88:91], v195 offset:5200
	v_pk_fma_f32 v[146:147], v[12:13], v[92:93], v[146:147] neg_lo:[1,0,0] neg_hi:[1,0,0]
	v_pk_fma_f32 v[148:149], v[14:15], v[94:95], v[148:149] neg_lo:[1,0,0] neg_hi:[1,0,0]
	ds_read_b128 v[92:95], v195 offset:5216
	s_waitcnt lgkmcnt(4)
	v_pk_fma_f32 v[146:147], v[16:17], v[96:97], v[146:147] neg_lo:[1,0,0] neg_hi:[1,0,0]
	ds_read_b128 v[96:99], v195 offset:5232
	v_add_f32_e32 v150, v147, v146
	v_add_f32_e32 v151, v148, v149
	v_add_f32_e32 v18, v151, v150
	v_cmp_eq_u32_e32 vcc, 19, v188
	s_nop 1
	v_cndmask_b32_e64 v202, 0, 1.0, vcc
	s_waitcnt lgkmcnt(1)
	v_pk_fma_f32 v[146:147], v[0:1], v[80:81], v[202:203] neg_lo:[1,0,0] neg_hi:[1,0,0]
	v_pk_fma_f32 v[148:149], v[2:3], v[82:83], v[200:201] neg_lo:[1,0,0] neg_hi:[1,0,0]
	ds_read_b128 v[80:83], v195 offset:5440
	v_pk_fma_f32 v[146:147], v[4:5], v[84:85], v[146:147] neg_lo:[1,0,0] neg_hi:[1,0,0]
	v_pk_fma_f32 v[148:149], v[6:7], v[86:87], v[148:149] neg_lo:[1,0,0] neg_hi:[1,0,0]
	ds_read_b128 v[84:87], v195 offset:5456
	v_pk_fma_f32 v[146:147], v[8:9], v[88:89], v[146:147] neg_lo:[1,0,0] neg_hi:[1,0,0]
	v_pk_fma_f32 v[148:149], v[10:11], v[90:91], v[148:149] neg_lo:[1,0,0] neg_hi:[1,0,0]
	ds_read_b128 v[88:91], v195 offset:5472
	v_pk_fma_f32 v[146:147], v[12:13], v[92:93], v[146:147] neg_lo:[1,0,0] neg_hi:[1,0,0]
	v_pk_fma_f32 v[148:149], v[14:15], v[94:95], v[148:149] neg_lo:[1,0,0] neg_hi:[1,0,0]
	ds_read_b128 v[92:95], v195 offset:5488
	s_waitcnt lgkmcnt(4)
	v_pk_fma_f32 v[146:147], v[16:17], v[96:97], v[146:147] neg_lo:[1,0,0] neg_hi:[1,0,0]
	v_fma_f32 v148, -v18, v98, v148
	ds_read_b128 v[96:99], v195 offset:5504
	v_add_f32_e32 v150, v147, v146
	v_add_f32_e32 v151, v148, v149
	v_add_f32_e32 v19, v151, v150
	v_cmp_eq_u32_e32 vcc, 20, v188
	s_nop 1
	v_cndmask_b32_e64 v202, 0, 1.0, vcc
	s_waitcnt lgkmcnt(1)
	v_pk_fma_f32 v[146:147], v[0:1], v[80:81], v[202:203] neg_lo:[1,0,0] neg_hi:[1,0,0]
	v_pk_fma_f32 v[148:149], v[2:3], v[82:83], v[200:201] neg_lo:[1,0,0] neg_hi:[1,0,0]
	ds_read_b128 v[80:83], v195 offset:5712
	v_pk_fma_f32 v[146:147], v[4:5], v[84:85], v[146:147] neg_lo:[1,0,0] neg_hi:[1,0,0]
	v_pk_fma_f32 v[148:149], v[6:7], v[86:87], v[148:149] neg_lo:[1,0,0] neg_hi:[1,0,0]
	ds_read_b128 v[84:87], v195 offset:5728
	v_pk_fma_f32 v[146:147], v[8:9], v[88:89], v[146:147] neg_lo:[1,0,0] neg_hi:[1,0,0]
	v_pk_fma_f32 v[148:149], v[10:11], v[90:91], v[148:149] neg_lo:[1,0,0] neg_hi:[1,0,0]
	ds_read_b128 v[88:91], v195 offset:5744
	v_pk_fma_f32 v[146:147], v[12:13], v[92:93], v[146:147] neg_lo:[1,0,0] neg_hi:[1,0,0]
	v_pk_fma_f32 v[148:149], v[14:15], v[94:95], v[148:149] neg_lo:[1,0,0] neg_hi:[1,0,0]
	ds_read_b128 v[92:95], v195 offset:5760
	s_waitcnt lgkmcnt(4)
	v_pk_fma_f32 v[146:147], v[16:17], v[96:97], v[146:147] neg_lo:[1,0,0] neg_hi:[1,0,0]
	v_pk_fma_f32 v[148:149], v[18:19], v[98:99], v[148:149] neg_lo:[1,0,0] neg_hi:[1,0,0]
	ds_read_b128 v[96:99], v195 offset:5776
	ds_read_b128 v[100:103], v195 offset:5792
	v_add_f32_e32 v150, v147, v146
	v_add_f32_e32 v151, v148, v149
	v_add_f32_e32 v20, v151, v150
	v_cmp_eq_u32_e32 vcc, 21, v188
	s_nop 1
	v_cndmask_b32_e64 v202, 0, 1.0, vcc
	s_waitcnt lgkmcnt(2)
	v_pk_fma_f32 v[146:147], v[0:1], v[80:81], v[202:203] neg_lo:[1,0,0] neg_hi:[1,0,0]
	v_pk_fma_f32 v[148:149], v[2:3], v[82:83], v[200:201] neg_lo:[1,0,0] neg_hi:[1,0,0]
	ds_read_b128 v[80:83], v195 offset:5984
	v_pk_fma_f32 v[146:147], v[4:5], v[84:85], v[146:147] neg_lo:[1,0,0] neg_hi:[1,0,0]
	v_pk_fma_f32 v[148:149], v[6:7], v[86:87], v[148:149] neg_lo:[1,0,0] neg_hi:[1,0,0]
	ds_read_b128 v[84:87], v195 offset:6000
	v_pk_fma_f32 v[146:147], v[8:9], v[88:89], v[146:147] neg_lo:[1,0,0] neg_hi:[1,0,0]
	v_pk_fma_f32 v[148:149], v[10:11], v[90:91], v[148:149] neg_lo:[1,0,0] neg_hi:[1,0,0]
	ds_read_b128 v[88:91], v195 offset:6016
	v_pk_fma_f32 v[146:147], v[12:13], v[92:93], v[146:147] neg_lo:[1,0,0] neg_hi:[1,0,0]
	v_pk_fma_f32 v[148:149], v[14:15], v[94:95], v[148:149] neg_lo:[1,0,0] neg_hi:[1,0,0]
	ds_read_b128 v[92:95], v195 offset:6032
	s_waitcnt lgkmcnt(4)
	v_pk_fma_f32 v[146:147], v[16:17], v[96:97], v[146:147] neg_lo:[1,0,0] neg_hi:[1,0,0]
	v_pk_fma_f32 v[148:149], v[18:19], v[98:99], v[148:149] neg_lo:[1,0,0] neg_hi:[1,0,0]
	ds_read_b128 v[96:99], v195 offset:6048
	v_fma_f32 v146, -v20, v100, v146
	ds_read_b128 v[100:103], v195 offset:6064
	v_add_f32_e32 v150, v147, v146
	v_add_f32_e32 v151, v148, v149
	v_add_f32_e32 v21, v151, v150
	v_cmp_eq_u32_e32 vcc, 22, v188
	s_nop 1
	v_cndmask_b32_e64 v202, 0, 1.0, vcc
	s_waitcnt lgkmcnt(2)
	v_pk_fma_f32 v[146:147], v[0:1], v[80:81], v[202:203] neg_lo:[1,0,0] neg_hi:[1,0,0]
	v_pk_fma_f32 v[148:149], v[2:3], v[82:83], v[200:201] neg_lo:[1,0,0] neg_hi:[1,0,0]
	ds_read_b128 v[80:83], v195 offset:6256
	v_pk_fma_f32 v[146:147], v[4:5], v[84:85], v[146:147] neg_lo:[1,0,0] neg_hi:[1,0,0]
	v_pk_fma_f32 v[148:149], v[6:7], v[86:87], v[148:149] neg_lo:[1,0,0] neg_hi:[1,0,0]
	ds_read_b128 v[84:87], v195 offset:6272
	v_pk_fma_f32 v[146:147], v[8:9], v[88:89], v[146:147] neg_lo:[1,0,0] neg_hi:[1,0,0]
	v_pk_fma_f32 v[148:149], v[10:11], v[90:91], v[148:149] neg_lo:[1,0,0] neg_hi:[1,0,0]
	ds_read_b128 v[88:91], v195 offset:6288
	v_pk_fma_f32 v[146:147], v[12:13], v[92:93], v[146:147] neg_lo:[1,0,0] neg_hi:[1,0,0]
	v_pk_fma_f32 v[148:149], v[14:15], v[94:95], v[148:149] neg_lo:[1,0,0] neg_hi:[1,0,0]
	ds_read_b128 v[92:95], v195 offset:6304
	s_waitcnt lgkmcnt(4)
	v_pk_fma_f32 v[146:147], v[16:17], v[96:97], v[146:147] neg_lo:[1,0,0] neg_hi:[1,0,0]
	v_pk_fma_f32 v[148:149], v[18:19], v[98:99], v[148:149] neg_lo:[1,0,0] neg_hi:[1,0,0]
	ds_read_b128 v[96:99], v195 offset:6320
	v_pk_fma_f32 v[146:147], v[20:21], v[100:101], v[146:147] neg_lo:[1,0,0] neg_hi:[1,0,0]
	ds_read_b128 v[100:103], v195 offset:6336
	v_add_f32_e32 v150, v147, v146
	v_add_f32_e32 v151, v148, v149
	v_add_f32_e32 v22, v151, v150
	v_cmp_eq_u32_e32 vcc, 23, v188
	s_nop 1
	v_cndmask_b32_e64 v202, 0, 1.0, vcc
	s_waitcnt lgkmcnt(2)
	v_pk_fma_f32 v[146:147], v[0:1], v[80:81], v[202:203] neg_lo:[1,0,0] neg_hi:[1,0,0]
	v_pk_fma_f32 v[148:149], v[2:3], v[82:83], v[200:201] neg_lo:[1,0,0] neg_hi:[1,0,0]
	ds_read_b128 v[80:83], v195 offset:6528
	v_pk_fma_f32 v[146:147], v[4:5], v[84:85], v[146:147] neg_lo:[1,0,0] neg_hi:[1,0,0]
	v_pk_fma_f32 v[148:149], v[6:7], v[86:87], v[148:149] neg_lo:[1,0,0] neg_hi:[1,0,0]
	ds_read_b128 v[84:87], v195 offset:6544
	v_pk_fma_f32 v[146:147], v[8:9], v[88:89], v[146:147] neg_lo:[1,0,0] neg_hi:[1,0,0]
	v_pk_fma_f32 v[148:149], v[10:11], v[90:91], v[148:149] neg_lo:[1,0,0] neg_hi:[1,0,0]
	ds_read_b128 v[88:91], v195 offset:6560
	v_pk_fma_f32 v[146:147], v[12:13], v[92:93], v[146:147] neg_lo:[1,0,0] neg_hi:[1,0,0]
	v_pk_fma_f32 v[148:149], v[14:15], v[94:95], v[148:149] neg_lo:[1,0,0] neg_hi:[1,0,0]
	ds_read_b128 v[92:95], v195 offset:6576
	s_waitcnt lgkmcnt(4)
	v_pk_fma_f32 v[146:147], v[16:17], v[96:97], v[146:147] neg_lo:[1,0,0] neg_hi:[1,0,0]
	v_pk_fma_f32 v[148:149], v[18:19], v[98:99], v[148:149] neg_lo:[1,0,0] neg_hi:[1,0,0]
	ds_read_b128 v[96:99], v195 offset:6592
	v_pk_fma_f32 v[146:147], v[20:21], v[100:101], v[146:147] neg_lo:[1,0,0] neg_hi:[1,0,0]
	v_fma_f32 v148, -v22, v102, v148
	ds_read_b128 v[100:103], v195 offset:6608
	v_add_f32_e32 v150, v147, v146
	v_add_f32_e32 v151, v148, v149
	v_add_f32_e32 v23, v151, v150
	v_cmp_eq_u32_e32 vcc, 24, v188
	s_nop 1
	v_cndmask_b32_e64 v202, 0, 1.0, vcc
	s_waitcnt lgkmcnt(2)
	v_pk_fma_f32 v[146:147], v[0:1], v[80:81], v[202:203] neg_lo:[1,0,0] neg_hi:[1,0,0]
	v_pk_fma_f32 v[148:149], v[2:3], v[82:83], v[200:201] neg_lo:[1,0,0] neg_hi:[1,0,0]
	ds_read_b128 v[80:83], v195 offset:6800
	v_pk_fma_f32 v[146:147], v[4:5], v[84:85], v[146:147] neg_lo:[1,0,0] neg_hi:[1,0,0]
	v_pk_fma_f32 v[148:149], v[6:7], v[86:87], v[148:149] neg_lo:[1,0,0] neg_hi:[1,0,0]
	ds_read_b128 v[84:87], v195 offset:6816
	v_pk_fma_f32 v[146:147], v[8:9], v[88:89], v[146:147] neg_lo:[1,0,0] neg_hi:[1,0,0]
	v_pk_fma_f32 v[148:149], v[10:11], v[90:91], v[148:149] neg_lo:[1,0,0] neg_hi:[1,0,0]
	ds_read_b128 v[88:91], v195 offset:6832
	v_pk_fma_f32 v[146:147], v[12:13], v[92:93], v[146:147] neg_lo:[1,0,0] neg_hi:[1,0,0]
	v_pk_fma_f32 v[148:149], v[14:15], v[94:95], v[148:149] neg_lo:[1,0,0] neg_hi:[1,0,0]
	ds_read_b128 v[92:95], v195 offset:6848
	s_waitcnt lgkmcnt(4)
	v_pk_fma_f32 v[146:147], v[16:17], v[96:97], v[146:147] neg_lo:[1,0,0] neg_hi:[1,0,0]
	v_pk_fma_f32 v[148:149], v[18:19], v[98:99], v[148:149] neg_lo:[1,0,0] neg_hi:[1,0,0]
	ds_read_b128 v[96:99], v195 offset:6864
	v_pk_fma_f32 v[146:147], v[20:21], v[100:101], v[146:147] neg_lo:[1,0,0] neg_hi:[1,0,0]
	v_pk_fma_f32 v[148:149], v[22:23], v[102:103], v[148:149] neg_lo:[1,0,0] neg_hi:[1,0,0]
	ds_read_b128 v[100:103], v195 offset:6880
	ds_read_b128 v[104:107], v195 offset:6896
	v_add_f32_e32 v150, v147, v146
	v_add_f32_e32 v151, v148, v149
	v_add_f32_e32 v24, v151, v150
	v_cmp_eq_u32_e32 vcc, 25, v188
	s_nop 1
	v_cndmask_b32_e64 v202, 0, 1.0, vcc
	s_waitcnt lgkmcnt(3)
	v_pk_fma_f32 v[146:147], v[0:1], v[80:81], v[202:203] neg_lo:[1,0,0] neg_hi:[1,0,0]
	v_pk_fma_f32 v[148:149], v[2:3], v[82:83], v[200:201] neg_lo:[1,0,0] neg_hi:[1,0,0]
	ds_read_b128 v[80:83], v195 offset:7072
	v_pk_fma_f32 v[146:147], v[4:5], v[84:85], v[146:147] neg_lo:[1,0,0] neg_hi:[1,0,0]
	v_pk_fma_f32 v[148:149], v[6:7], v[86:87], v[148:149] neg_lo:[1,0,0] neg_hi:[1,0,0]
	ds_read_b128 v[84:87], v195 offset:7088
	v_pk_fma_f32 v[146:147], v[8:9], v[88:89], v[146:147] neg_lo:[1,0,0] neg_hi:[1,0,0]
	v_pk_fma_f32 v[148:149], v[10:11], v[90:91], v[148:149] neg_lo:[1,0,0] neg_hi:[1,0,0]
	ds_read_b128 v[88:91], v195 offset:7104
	v_pk_fma_f32 v[146:147], v[12:13], v[92:93], v[146:147] neg_lo:[1,0,0] neg_hi:[1,0,0]
	v_pk_fma_f32 v[148:149], v[14:15], v[94:95], v[148:149] neg_lo:[1,0,0] neg_hi:[1,0,0]
	ds_read_b128 v[92:95], v195 offset:7120
	s_waitcnt lgkmcnt(4)
	v_pk_fma_f32 v[146:147], v[16:17], v[96:97], v[146:147] neg_lo:[1,0,0] neg_hi:[1,0,0]
	v_pk_fma_f32 v[148:149], v[18:19], v[98:99], v[148:149] neg_lo:[1,0,0] neg_hi:[1,0,0]
	ds_read_b128 v[96:99], v195 offset:7136
	v_pk_fma_f32 v[146:147], v[20:21], v[100:101], v[146:147] neg_lo:[1,0,0] neg_hi:[1,0,0]
	v_pk_fma_f32 v[148:149], v[22:23], v[102:103], v[148:149] neg_lo:[1,0,0] neg_hi:[1,0,0]
	ds_read_b128 v[100:103], v195 offset:7152
	v_fma_f32 v146, -v24, v104, v146
	ds_read_b128 v[104:107], v195 offset:7168
	v_add_f32_e32 v150, v147, v146
	v_add_f32_e32 v151, v148, v149
	v_add_f32_e32 v25, v151, v150
	v_cmp_eq_u32_e32 vcc, 26, v188
	s_nop 1
	v_cndmask_b32_e64 v202, 0, 1.0, vcc
	s_waitcnt lgkmcnt(3)
	v_pk_fma_f32 v[146:147], v[0:1], v[80:81], v[202:203] neg_lo:[1,0,0] neg_hi:[1,0,0]
	v_pk_fma_f32 v[148:149], v[2:3], v[82:83], v[200:201] neg_lo:[1,0,0] neg_hi:[1,0,0]
	ds_read_b128 v[80:83], v195 offset:7344
	v_pk_fma_f32 v[146:147], v[4:5], v[84:85], v[146:147] neg_lo:[1,0,0] neg_hi:[1,0,0]
	v_pk_fma_f32 v[148:149], v[6:7], v[86:87], v[148:149] neg_lo:[1,0,0] neg_hi:[1,0,0]
	ds_read_b128 v[84:87], v195 offset:7360
	v_pk_fma_f32 v[146:147], v[8:9], v[88:89], v[146:147] neg_lo:[1,0,0] neg_hi:[1,0,0]
	v_pk_fma_f32 v[148:149], v[10:11], v[90:91], v[148:149] neg_lo:[1,0,0] neg_hi:[1,0,0]
	ds_read_b128 v[88:91], v195 offset:7376
	v_pk_fma_f32 v[146:147], v[12:13], v[92:93], v[146:147] neg_lo:[1,0,0] neg_hi:[1,0,0]
	v_pk_fma_f32 v[148:149], v[14:15], v[94:95], v[148:149] neg_lo:[1,0,0] neg_hi:[1,0,0]
	ds_read_b128 v[92:95], v195 offset:7392
	s_waitcnt lgkmcnt(4)
	v_pk_fma_f32 v[146:147], v[16:17], v[96:97], v[146:147] neg_lo:[1,0,0] neg_hi:[1,0,0]
	v_pk_fma_f32 v[148:149], v[18:19], v[98:99], v[148:149] neg_lo:[1,0,0] neg_hi:[1,0,0]
	ds_read_b128 v[96:99], v195 offset:7408
	v_pk_fma_f32 v[146:147], v[20:21], v[100:101], v[146:147] neg_lo:[1,0,0] neg_hi:[1,0,0]
	v_pk_fma_f32 v[148:149], v[22:23], v[102:103], v[148:149] neg_lo:[1,0,0] neg_hi:[1,0,0]
	ds_read_b128 v[100:103], v195 offset:7424
	v_pk_fma_f32 v[146:147], v[24:25], v[104:105], v[146:147] neg_lo:[1,0,0] neg_hi:[1,0,0]
	ds_read_b128 v[104:107], v195 offset:7440
	v_add_f32_e32 v150, v147, v146
	v_add_f32_e32 v151, v148, v149
	v_add_f32_e32 v26, v151, v150
	v_cmp_eq_u32_e32 vcc, 27, v188
	s_nop 1
	v_cndmask_b32_e64 v202, 0, 1.0, vcc
	s_waitcnt lgkmcnt(3)
	v_pk_fma_f32 v[146:147], v[0:1], v[80:81], v[202:203] neg_lo:[1,0,0] neg_hi:[1,0,0]
	v_pk_fma_f32 v[148:149], v[2:3], v[82:83], v[200:201] neg_lo:[1,0,0] neg_hi:[1,0,0]
	ds_read_b128 v[80:83], v195 offset:7616
	v_pk_fma_f32 v[146:147], v[4:5], v[84:85], v[146:147] neg_lo:[1,0,0] neg_hi:[1,0,0]
	v_pk_fma_f32 v[148:149], v[6:7], v[86:87], v[148:149] neg_lo:[1,0,0] neg_hi:[1,0,0]
	ds_read_b128 v[84:87], v195 offset:7632
	v_pk_fma_f32 v[146:147], v[8:9], v[88:89], v[146:147] neg_lo:[1,0,0] neg_hi:[1,0,0]
	v_pk_fma_f32 v[148:149], v[10:11], v[90:91], v[148:149] neg_lo:[1,0,0] neg_hi:[1,0,0]
	ds_read_b128 v[88:91], v195 offset:7648
	v_pk_fma_f32 v[146:147], v[12:13], v[92:93], v[146:147] neg_lo:[1,0,0] neg_hi:[1,0,0]
	v_pk_fma_f32 v[148:149], v[14:15], v[94:95], v[148:149] neg_lo:[1,0,0] neg_hi:[1,0,0]
	ds_read_b128 v[92:95], v195 offset:7664
	s_waitcnt lgkmcnt(4)
	v_pk_fma_f32 v[146:147], v[16:17], v[96:97], v[146:147] neg_lo:[1,0,0] neg_hi:[1,0,0]
	v_pk_fma_f32 v[148:149], v[18:19], v[98:99], v[148:149] neg_lo:[1,0,0] neg_hi:[1,0,0]
	ds_read_b128 v[96:99], v195 offset:7680
	v_pk_fma_f32 v[146:147], v[20:21], v[100:101], v[146:147] neg_lo:[1,0,0] neg_hi:[1,0,0]
	v_pk_fma_f32 v[148:149], v[22:23], v[102:103], v[148:149] neg_lo:[1,0,0] neg_hi:[1,0,0]
	ds_read_b128 v[100:103], v195 offset:7696
	v_pk_fma_f32 v[146:147], v[24:25], v[104:105], v[146:147] neg_lo:[1,0,0] neg_hi:[1,0,0]
	v_fma_f32 v148, -v26, v106, v148
	ds_read_b128 v[104:107], v195 offset:7712
	v_add_f32_e32 v150, v147, v146
	v_add_f32_e32 v151, v148, v149
	v_add_f32_e32 v27, v151, v150
	v_cmp_eq_u32_e32 vcc, 28, v188
	s_nop 1
	v_cndmask_b32_e64 v202, 0, 1.0, vcc
	s_waitcnt lgkmcnt(3)
	v_pk_fma_f32 v[146:147], v[0:1], v[80:81], v[202:203] neg_lo:[1,0,0] neg_hi:[1,0,0]
	v_pk_fma_f32 v[148:149], v[2:3], v[82:83], v[200:201] neg_lo:[1,0,0] neg_hi:[1,0,0]
	ds_read_b128 v[80:83], v195 offset:7888
	v_pk_fma_f32 v[146:147], v[4:5], v[84:85], v[146:147] neg_lo:[1,0,0] neg_hi:[1,0,0]
	v_pk_fma_f32 v[148:149], v[6:7], v[86:87], v[148:149] neg_lo:[1,0,0] neg_hi:[1,0,0]
	ds_read_b128 v[84:87], v195 offset:7904
	v_pk_fma_f32 v[146:147], v[8:9], v[88:89], v[146:147] neg_lo:[1,0,0] neg_hi:[1,0,0]
	v_pk_fma_f32 v[148:149], v[10:11], v[90:91], v[148:149] neg_lo:[1,0,0] neg_hi:[1,0,0]
	ds_read_b128 v[88:91], v195 offset:7920
	v_pk_fma_f32 v[146:147], v[12:13], v[92:93], v[146:147] neg_lo:[1,0,0] neg_hi:[1,0,0]
	v_pk_fma_f32 v[148:149], v[14:15], v[94:95], v[148:149] neg_lo:[1,0,0] neg_hi:[1,0,0]
	ds_read_b128 v[92:95], v195 offset:7936
	s_waitcnt lgkmcnt(4)
	v_pk_fma_f32 v[146:147], v[16:17], v[96:97], v[146:147] neg_lo:[1,0,0] neg_hi:[1,0,0]
	v_pk_fma_f32 v[148:149], v[18:19], v[98:99], v[148:149] neg_lo:[1,0,0] neg_hi:[1,0,0]
	ds_read_b128 v[96:99], v195 offset:7952
	v_pk_fma_f32 v[146:147], v[20:21], v[100:101], v[146:147] neg_lo:[1,0,0] neg_hi:[1,0,0]
	v_pk_fma_f32 v[148:149], v[22:23], v[102:103], v[148:149] neg_lo:[1,0,0] neg_hi:[1,0,0]
	ds_read_b128 v[100:103], v195 offset:7968
	v_pk_fma_f32 v[146:147], v[24:25], v[104:105], v[146:147] neg_lo:[1,0,0] neg_hi:[1,0,0]
	v_pk_fma_f32 v[148:149], v[26:27], v[106:107], v[148:149] neg_lo:[1,0,0] neg_hi:[1,0,0]
	ds_read_b128 v[104:107], v195 offset:7984
	ds_read_b128 v[108:111], v195 offset:8000
	v_add_f32_e32 v150, v147, v146
	v_add_f32_e32 v151, v148, v149
	v_add_f32_e32 v28, v151, v150
	v_cmp_eq_u32_e32 vcc, 29, v188
	s_nop 1
	v_cndmask_b32_e64 v202, 0, 1.0, vcc
	s_waitcnt lgkmcnt(4)
	v_pk_fma_f32 v[146:147], v[0:1], v[80:81], v[202:203] neg_lo:[1,0,0] neg_hi:[1,0,0]
	v_pk_fma_f32 v[148:149], v[2:3], v[82:83], v[200:201] neg_lo:[1,0,0] neg_hi:[1,0,0]
	ds_read_b128 v[80:83], v195 offset:8160
	v_pk_fma_f32 v[146:147], v[4:5], v[84:85], v[146:147] neg_lo:[1,0,0] neg_hi:[1,0,0]
	v_pk_fma_f32 v[148:149], v[6:7], v[86:87], v[148:149] neg_lo:[1,0,0] neg_hi:[1,0,0]
	ds_read_b128 v[84:87], v195 offset:8176
	v_pk_fma_f32 v[146:147], v[8:9], v[88:89], v[146:147] neg_lo:[1,0,0] neg_hi:[1,0,0]
	v_pk_fma_f32 v[148:149], v[10:11], v[90:91], v[148:149] neg_lo:[1,0,0] neg_hi:[1,0,0]
	ds_read_b128 v[88:91], v195 offset:8192
	v_pk_fma_f32 v[146:147], v[12:13], v[92:93], v[146:147] neg_lo:[1,0,0] neg_hi:[1,0,0]
	v_pk_fma_f32 v[148:149], v[14:15], v[94:95], v[148:149] neg_lo:[1,0,0] neg_hi:[1,0,0]
	ds_read_b128 v[92:95], v195 offset:8208
	s_waitcnt lgkmcnt(4)
	v_pk_fma_f32 v[146:147], v[16:17], v[96:97], v[146:147] neg_lo:[1,0,0] neg_hi:[1,0,0]
	v_pk_fma_f32 v[148:149], v[18:19], v[98:99], v[148:149] neg_lo:[1,0,0] neg_hi:[1,0,0]
	ds_read_b128 v[96:99], v195 offset:8224
	v_pk_fma_f32 v[146:147], v[20:21], v[100:101], v[146:147] neg_lo:[1,0,0] neg_hi:[1,0,0]
	v_pk_fma_f32 v[148:149], v[22:23], v[102:103], v[148:149] neg_lo:[1,0,0] neg_hi:[1,0,0]
	ds_read_b128 v[100:103], v195 offset:8240
	v_pk_fma_f32 v[146:147], v[24:25], v[104:105], v[146:147] neg_lo:[1,0,0] neg_hi:[1,0,0]
	v_pk_fma_f32 v[148:149], v[26:27], v[106:107], v[148:149] neg_lo:[1,0,0] neg_hi:[1,0,0]
	ds_read_b128 v[104:107], v195 offset:8256
	v_fma_f32 v146, -v28, v108, v146
	ds_read_b128 v[108:111], v195 offset:8272
	v_add_f32_e32 v150, v147, v146
	v_add_f32_e32 v151, v148, v149
	v_add_f32_e32 v29, v151, v150
	v_cmp_eq_u32_e32 vcc, 30, v188
	s_nop 1
	v_cndmask_b32_e64 v202, 0, 1.0, vcc
	s_waitcnt lgkmcnt(4)
	v_pk_fma_f32 v[146:147], v[0:1], v[80:81], v[202:203] neg_lo:[1,0,0] neg_hi:[1,0,0]
	v_pk_fma_f32 v[148:149], v[2:3], v[82:83], v[200:201] neg_lo:[1,0,0] neg_hi:[1,0,0]
	ds_read_b128 v[80:83], v195 offset:8432
	v_pk_fma_f32 v[146:147], v[4:5], v[84:85], v[146:147] neg_lo:[1,0,0] neg_hi:[1,0,0]
	v_pk_fma_f32 v[148:149], v[6:7], v[86:87], v[148:149] neg_lo:[1,0,0] neg_hi:[1,0,0]
	ds_read_b128 v[84:87], v195 offset:8448
	v_pk_fma_f32 v[146:147], v[8:9], v[88:89], v[146:147] neg_lo:[1,0,0] neg_hi:[1,0,0]
	v_pk_fma_f32 v[148:149], v[10:11], v[90:91], v[148:149] neg_lo:[1,0,0] neg_hi:[1,0,0]
	ds_read_b128 v[88:91], v195 offset:8464
	v_pk_fma_f32 v[146:147], v[12:13], v[92:93], v[146:147] neg_lo:[1,0,0] neg_hi:[1,0,0]
	v_pk_fma_f32 v[148:149], v[14:15], v[94:95], v[148:149] neg_lo:[1,0,0] neg_hi:[1,0,0]
	ds_read_b128 v[92:95], v195 offset:8480
	s_waitcnt lgkmcnt(4)
	v_pk_fma_f32 v[146:147], v[16:17], v[96:97], v[146:147] neg_lo:[1,0,0] neg_hi:[1,0,0]
	v_pk_fma_f32 v[148:149], v[18:19], v[98:99], v[148:149] neg_lo:[1,0,0] neg_hi:[1,0,0]
	ds_read_b128 v[96:99], v195 offset:8496
	v_pk_fma_f32 v[146:147], v[20:21], v[100:101], v[146:147] neg_lo:[1,0,0] neg_hi:[1,0,0]
	v_pk_fma_f32 v[148:149], v[22:23], v[102:103], v[148:149] neg_lo:[1,0,0] neg_hi:[1,0,0]
	ds_read_b128 v[100:103], v195 offset:8512
	v_pk_fma_f32 v[146:147], v[24:25], v[104:105], v[146:147] neg_lo:[1,0,0] neg_hi:[1,0,0]
	v_pk_fma_f32 v[148:149], v[26:27], v[106:107], v[148:149] neg_lo:[1,0,0] neg_hi:[1,0,0]
	ds_read_b128 v[104:107], v195 offset:8528
	v_pk_fma_f32 v[146:147], v[28:29], v[108:109], v[146:147] neg_lo:[1,0,0] neg_hi:[1,0,0]
	ds_read_b128 v[108:111], v195 offset:8544
	v_add_f32_e32 v150, v147, v146
	v_add_f32_e32 v151, v148, v149
	v_add_f32_e32 v30, v151, v150
	v_cmp_eq_u32_e32 vcc, 31, v188
	s_nop 1
	v_cndmask_b32_e64 v202, 0, 1.0, vcc
	s_waitcnt lgkmcnt(4)
	v_pk_fma_f32 v[146:147], v[0:1], v[80:81], v[202:203] neg_lo:[1,0,0] neg_hi:[1,0,0]
	v_pk_fma_f32 v[148:149], v[2:3], v[82:83], v[200:201] neg_lo:[1,0,0] neg_hi:[1,0,0]
	v_pk_fma_f32 v[146:147], v[4:5], v[84:85], v[146:147] neg_lo:[1,0,0] neg_hi:[1,0,0]
	v_pk_fma_f32 v[148:149], v[6:7], v[86:87], v[148:149] neg_lo:[1,0,0] neg_hi:[1,0,0]
	v_pk_fma_f32 v[146:147], v[8:9], v[88:89], v[146:147] neg_lo:[1,0,0] neg_hi:[1,0,0]
	v_pk_fma_f32 v[148:149], v[10:11], v[90:91], v[148:149] neg_lo:[1,0,0] neg_hi:[1,0,0]
	v_pk_fma_f32 v[146:147], v[12:13], v[92:93], v[146:147] neg_lo:[1,0,0] neg_hi:[1,0,0]
	v_pk_fma_f32 v[148:149], v[14:15], v[94:95], v[148:149] neg_lo:[1,0,0] neg_hi:[1,0,0]
	s_waitcnt lgkmcnt(0)
	v_pk_fma_f32 v[146:147], v[16:17], v[96:97], v[146:147] neg_lo:[1,0,0] neg_hi:[1,0,0]
	v_pk_fma_f32 v[148:149], v[18:19], v[98:99], v[148:149] neg_lo:[1,0,0] neg_hi:[1,0,0]
	v_pk_fma_f32 v[146:147], v[20:21], v[100:101], v[146:147] neg_lo:[1,0,0] neg_hi:[1,0,0]
	v_pk_fma_f32 v[148:149], v[22:23], v[102:103], v[148:149] neg_lo:[1,0,0] neg_hi:[1,0,0]
	v_pk_fma_f32 v[146:147], v[24:25], v[104:105], v[146:147] neg_lo:[1,0,0] neg_hi:[1,0,0]
	v_pk_fma_f32 v[148:149], v[26:27], v[106:107], v[148:149] neg_lo:[1,0,0] neg_hi:[1,0,0]
	v_pk_fma_f32 v[146:147], v[28:29], v[108:109], v[146:147] neg_lo:[1,0,0] neg_hi:[1,0,0]
	v_fma_f32 v148, -v30, v110, v148
	v_add_f32_e32 v150, v147, v146
	v_add_f32_e32 v151, v148, v149
	v_add_f32_e32 v31, v151, v150
	v_mul_u32_u24_e32 v204, 0x110, v188
	v_lshl_add_u32 v204, v189, 2, v204
	v_add_u32_e32 v204, 0x2200, v204
	v_add_u32_e32 v196, v194, v204
	v_mul_u32_u24_e32 v204, 132, v188
	v_lshl_add_u32 v204, v189, 2, v204
	v_add_u32_e32 v197, s0, v204
	v_mul_u32_u24_e32 v204, 132, v189
	v_add3_u32 v198, v204, v199, s0
	s_nop 1
	v_permlane32_swap_b32_e32 v0, v1
	v_permlane32_swap_b32_e32 v2, v3
	v_permlane32_swap_b32_e32 v4, v5
	v_permlane32_swap_b32_e32 v6, v7
	v_permlane32_swap_b32_e32 v8, v9
	v_permlane32_swap_b32_e32 v10, v11
	v_permlane32_swap_b32_e32 v12, v13
	v_permlane32_swap_b32_e32 v14, v15
	v_permlane32_swap_b32_e32 v16, v17
	v_permlane32_swap_b32_e32 v18, v19
	v_permlane32_swap_b32_e32 v20, v21
	v_permlane32_swap_b32_e32 v22, v23
	v_permlane32_swap_b32_e32 v24, v25
	v_permlane32_swap_b32_e32 v26, v27
	v_permlane32_swap_b32_e32 v28, v29
	v_permlane32_swap_b32_e32 v30, v31
	ds_read2_b32 v[32:33], v196 offset0:0 offset1:2
	ds_read2_b32 v[34:35], v196 offset0:4 offset1:6
	ds_read2_b32 v[36:37], v196 offset0:8 offset1:10
	ds_read2_b32 v[38:39], v196 offset0:12 offset1:14
	ds_read2_b32 v[40:41], v196 offset0:16 offset1:18
	ds_read2_b32 v[42:43], v196 offset0:20 offset1:22
	ds_read2_b32 v[44:45], v196 offset0:24 offset1:26
	ds_read2_b32 v[46:47], v196 offset0:28 offset1:30
	v_xor_b32_e32 v204, 0x80000000, v1
	ds_write_b32 v198, v204
	v_xor_b32_e32 v205, 0x80000000, v3
	ds_write_b32 v198, v205 offset:264
	v_xor_b32_e32 v204, 0x80000000, v5
	ds_write_b32 v198, v204 offset:528
	v_xor_b32_e32 v205, 0x80000000, v7
	ds_write_b32 v198, v205 offset:792
	v_xor_b32_e32 v204, 0x80000000, v9
	ds_write_b32 v198, v204 offset:1056
	v_xor_b32_e32 v205, 0x80000000, v11
	ds_write_b32 v198, v205 offset:1320
	v_xor_b32_e32 v204, 0x80000000, v13
	ds_write_b32 v198, v204 offset:1584
	v_xor_b32_e32 v205, 0x80000000, v15
	s_waitcnt lgkmcnt(14)
	ds_write_b32 v198, v205 offset:1848
	v_xor_b32_e32 v204, 0x80000000, v17
	s_waitcnt lgkmcnt(14)
	ds_write_b32 v198, v204 offset:2112
	v_xor_b32_e32 v205, 0x80000000, v19
	s_waitcnt lgkmcnt(14)
	ds_write_b32 v198, v205 offset:2376
	v_xor_b32_e32 v204, 0x80000000, v21
	s_waitcnt lgkmcnt(14)
	ds_write_b32 v198, v204 offset:2640
	v_xor_b32_e32 v205, 0x80000000, v23
	s_waitcnt lgkmcnt(14)
	ds_write_b32 v198, v205 offset:2904
	v_xor_b32_e32 v204, 0x80000000, v25
	s_waitcnt lgkmcnt(14)
	ds_write_b32 v198, v204 offset:3168
	v_xor_b32_e32 v205, 0x80000000, v27
	s_waitcnt lgkmcnt(14)
	ds_write_b32 v198, v205 offset:3432
	v_xor_b32_e32 v204, 0x80000000, v29
	s_waitcnt lgkmcnt(14)
	ds_write_b32 v198, v204 offset:3696
	v_xor_b32_e32 v205, 0x80000000, v31
	s_waitcnt lgkmcnt(14)
	ds_write_b32 v198, v205 offset:3960
	s_waitcnt lgkmcnt(14)
	ds_read2_b32 v[48:49], v197 offset0:0 offset1:2
	s_waitcnt lgkmcnt(14)
	ds_read2_b32 v[50:51], v197 offset0:4 offset1:6
	s_waitcnt lgkmcnt(14)
	ds_read2_b32 v[52:53], v197 offset0:8 offset1:10
	s_waitcnt lgkmcnt(14)
	ds_read2_b32 v[54:55], v197 offset0:12 offset1:14
	s_waitcnt lgkmcnt(14)
	ds_read2_b32 v[56:57], v197 offset0:16 offset1:18
	s_waitcnt lgkmcnt(14)
	ds_read2_b32 v[58:59], v197 offset0:20 offset1:22
	s_waitcnt lgkmcnt(14)
	ds_read2_b32 v[60:61], v197 offset0:24 offset1:26
	s_waitcnt lgkmcnt(14)
	ds_read2_b32 v[62:63], v197 offset0:28 offset1:30
	v_mfma_f32_32x32x2_f32 v[64:79], v32, v0, 0
	v_mfma_f32_32x32x2_f32 v[64:79], v33, v2, v[64:79]
	v_mfma_f32_32x32x2_f32 v[64:79], v34, v4, v[64:79]
	v_mfma_f32_32x32x2_f32 v[64:79], v35, v6, v[64:79]
	v_mfma_f32_32x32x2_f32 v[64:79], v36, v8, v[64:79]
	v_mfma_f32_32x32x2_f32 v[64:79], v37, v10, v[64:79]
	v_mfma_f32_32x32x2_f32 v[64:79], v38, v12, v[64:79]
	v_mfma_f32_32x32x2_f32 v[64:79], v39, v14, v[64:79]
	v_mfma_f32_32x32x2_f32 v[64:79], v40, v16, v[64:79]
	v_mfma_f32_32x32x2_f32 v[64:79], v41, v18, v[64:79]
	v_mfma_f32_32x32x2_f32 v[64:79], v42, v20, v[64:79]
	v_mfma_f32_32x32x2_f32 v[64:79], v43, v22, v[64:79]
	v_mfma_f32_32x32x2_f32 v[64:79], v44, v24, v[64:79]
	v_mfma_f32_32x32x2_f32 v[64:79], v45, v26, v[64:79]
	v_mfma_f32_32x32x2_f32 v[64:79], v46, v28, v[64:79]
	v_mfma_f32_32x32x2_f32 v[64:79], v47, v30, v[64:79]
	s_cmp_lg_u32 s87, 0
	s_cbranch_scc1 .Ltri3_dg_b
	v_mul_u32_u24_e32 v204, 0x110, v189
	v_add3_u32 v204, v204, v199, v194
	ds_write_b32 v204, v0
	ds_write_b32 v204, v1 offset:8832
	ds_write_b32 v204, v2 offset:544
	ds_write_b32 v204, v3 offset:9376
	ds_write_b32 v204, v4 offset:1088
	ds_write_b32 v204, v5 offset:9920
	ds_write_b32 v204, v6 offset:1632
	ds_write_b32 v204, v7 offset:10464
	ds_write_b32 v204, v8 offset:2176
	ds_write_b32 v204, v9 offset:11008
	ds_write_b32 v204, v10 offset:2720
	ds_write_b32 v204, v11 offset:11552
	ds_write_b32 v204, v12 offset:3264
	ds_write_b32 v204, v13 offset:12096
	ds_write_b32 v204, v14 offset:3808
	ds_write_b32 v204, v15 offset:12640
	ds_write_b32 v204, v16 offset:4352
	ds_write_b32 v204, v17 offset:13184
	ds_write_b32 v204, v18 offset:4896
	ds_write_b32 v204, v19 offset:13728
	ds_write_b32 v204, v20 offset:5440
	ds_write_b32 v204, v21 offset:14272
	ds_write_b32 v204, v22 offset:5984
	ds_write_b32 v204, v23 offset:14816
	ds_write_b32 v204, v24 offset:6528
	ds_write_b32 v204, v25 offset:15360
	ds_write_b32 v204, v26 offset:7072
	ds_write_b32 v204, v27 offset:15904
	ds_write_b32 v204, v28 offset:7616
	ds_write_b32 v204, v29 offset:16448
	ds_write_b32 v204, v30 offset:8160
	ds_write_b32 v204, v31 offset:16992
	s_branch .Ltri3_dg_done
